# v52 with pair order srcA-major (4 consecutive same-accumulator pairs share the srcA fragment pair) in all four GEMM loops
# baseline (speedup 1.0000x reference)
; #define PG8_BAR __builtin_amdgcn_s_barrier()
; template <class Epi, class Sched, bool ALIGN_EPI = false, bool SP2 = false>
; __device__ __forceinline__ void gemm_phase(PG8_LAS unsigned char* lds, const Gemm g, const Sched& S, const Epi& E) {
;     ...
;     Unit cur, nxt; int ui = 0;
;     if (!S.next(0, cur)) return;
;     f32x4 acc[2][2][4][2];
; #pragma unroll
;     for (int a = 0; a < 2; ++a)
; #pragma unroll
;         for (int b = 0; b < 2; ++b)
; #pragma unroll
;             for (int m = 0; m < 4; ++m)
; #pragma unroll
;                 for (int n = 0; n < 2; ++n) acc[a][b][m][n] = (f32x4){0.f, 0.f, 0.f, 0.f};
;     bf16x8 At[4][2], B0[2][2], B1[2][2];
;     const char* cA; const char* cB; S.bases(cur, g, tstep, cA, cB);
;     S.a_ready(cur);
;     if constexpr (SP2) {
;         PG8_STAGE(PG8_SB(0, 0), cB, voffB); PG8_STAGE(PG8_SB(0, 1), cB + hstep, voffB); PG8_STAGE(PG8_SA(0, 0), cA, voffA); PG8_STAGE(PG8_SA(0, 1), cA + hstep, voffA);
;         if (wr == 1) PG8_BAR;
;         PG8_WAIT_V(2); PG8_BAR;
;         PG8_STAGE(PG8_SB(1, 0), cB + kstep, voffB); PG8_STAGE(PG8_SA(1, 0), cA + kstep, voffA); PG8_STAGE(PG8_SB(1, 1), cB + hstep + kstep, voffB);
;         PG8_WAIT_V(6); PG8_BAR;
;     } else {
;         PG8_STAGE(PG8_SB(0, 0), cB, voffB); PG8_STAGE(PG8_SA(0, 0), cA, voffA); PG8_STAGE(PG8_SB(0, 1), cB + hstep, voffB); PG8_STAGE(PG8_SA(0, 1), cA + hstep, voffA);
;         if (wr == 1) PG8_BAR;
;         PG8_WAIT_V(4); PG8_BAR;
;         PG8_STAGE(PG8_SB(1, 0), cB + kstep, voffB); PG8_STAGE(PG8_SA(1, 0), cA + kstep, voffA); PG8_STAGE(PG8_SB(1, 1), cB + hstep + kstep, voffB);
;         PG8_WAIT_V(6); PG8_BAR;
;     }
;     for (;;) {
;         const bool has_next = S.next(ui + 1, nxt);
;         const char* nA = cA; const char* nB = cB; if (has_next) S.bases(nxt, g, tstep, nA, nB);
;         for (int t = 0; t < nt; t += 2) {
;             const bool last = (t == nt - 2);
;             const char* a1 = cA + (size_t)(t + 1) * kstep;
;             const char* a2 = last ? nA : cA + (size_t)(t + 2) * kstep; const char* b2 = last ? nB : cB + (size_t)(t + 2) * kstep;
;             const char* a3 = a2 + kstep; const char* b3 = b2 + kstep;
;             if (last && has_next) S.a_ready(nxt);
;             if constexpr (Epi::MIDK) { if (t == (nt >> 1)) { E.midk(acc, wr, fr); asm volatile("s_waitcnt lgkmcnt(0)" ::: "memory"); } }
;             if constexpr (SP2) {
.LBB0_349:
	ds_read_b128 v[150:153], v169
	ds_read_b128 v[154:157], v169 offset:1024
	ds_read_b128 v[158:161], v169 offset:2048
	ds_read_b128 v[162:165], v169 offset:3072
	ds_read_b128 v[174:177], v170
	ds_read_b128 v[178:181], v170 offset:1024
	ds_read_b128 v[182:185], v170 offset:2048
	ds_read_b128 v[186:189], v170 offset:3072
	s_add_u32 s0, s88, 0xfff00080
	s_addc_u32 s1, s89, -1
	s_cmp_eq_u32 s23, 60
	s_cselect_b32 s93, s51, s1
	s_cselect_b32 s92, s50, s0
	s_cselect_b32 s91, s53, s21
	s_cselect_b32 s90, s52, s9
	ds_read_b128 v[190:193], v171
	ds_read_b128 v[196:199], v171 offset:1024
	ds_read_b128 v[200:203], v171 offset:2048
	ds_read_b128 v[204:207], v171 offset:3072
	ds_read_b128 v[208:211], v171 offset:4096
	ds_read_b128 v[212:215], v171 offset:5120
	ds_read_b128 v[220:223], v171 offset:6144
	ds_read_b128 v[224:227], v171 offset:7168
	s_add_u32 s0, s88, 0xfff00000
	s_addc_u32 s1, s89, -1
	s_add_i32 m0, s27, 0x8000
	s_nop 0
	global_load_lds_dwordx4 v134, s[0:1]
	s_add_i32 m0, s27, 0xa000
	s_nop 0
	global_load_lds_dwordx4 v138, s[0:1]
	s_add_i32 m0, s27, 0xc000
	s_nop 0
	global_load_lds_dwordx4 v134, s[88:89]
	s_add_i32 m0, s27, 0xe000
	s_nop 0
	global_load_lds_dwordx4 v138, s[88:89]
	s_waitcnt lgkmcnt(0)
	s_setprio 1
	v_mfma_f32_16x16x32_bf16 v[38:41], v[150:153], v[190:193], v[38:41]
	v_mfma_f32_16x16x32_bf16 v[38:41], v[154:157], v[196:199], v[38:41]
	v_mfma_f32_16x16x32_bf16 v[130:133], v[150:153], v[200:203], v[130:133]
	v_mfma_f32_16x16x32_bf16 v[130:133], v[154:157], v[204:207], v[130:133]
	v_mfma_f32_16x16x32_bf16 v[114:117], v[150:153], v[208:211], v[114:117]
	v_mfma_f32_16x16x32_bf16 v[114:117], v[154:157], v[212:215], v[114:117]
	v_mfma_f32_16x16x32_bf16 v[98:101], v[150:153], v[220:223], v[98:101]
	v_mfma_f32_16x16x32_bf16 v[98:101], v[154:157], v[224:227], v[98:101]
	v_mfma_f32_16x16x32_bf16 v[30:33], v[158:161], v[190:193], v[30:33]
	v_mfma_f32_16x16x32_bf16 v[30:33], v[162:165], v[196:199], v[30:33]
	v_mfma_f32_16x16x32_bf16 v[126:129], v[158:161], v[200:203], v[126:129]
	v_mfma_f32_16x16x32_bf16 v[126:129], v[162:165], v[204:207], v[126:129]
	v_mfma_f32_16x16x32_bf16 v[110:113], v[158:161], v[208:211], v[110:113]
	v_mfma_f32_16x16x32_bf16 v[110:113], v[162:165], v[212:215], v[110:113]
	v_mfma_f32_16x16x32_bf16 v[94:97], v[158:161], v[220:223], v[94:97]
	v_mfma_f32_16x16x32_bf16 v[94:97], v[162:165], v[224:227], v[94:97]
	v_mfma_f32_16x16x32_bf16 v[50:53], v[174:177], v[190:193], v[50:53]
	v_mfma_f32_16x16x32_bf16 v[50:53], v[178:181], v[196:199], v[50:53]
	v_mfma_f32_16x16x32_bf16 v[122:125], v[174:177], v[200:203], v[122:125]
	v_mfma_f32_16x16x32_bf16 v[122:125], v[178:181], v[204:207], v[122:125]
	v_mfma_f32_16x16x32_bf16 v[106:109], v[174:177], v[208:211], v[106:109]
	v_mfma_f32_16x16x32_bf16 v[106:109], v[178:181], v[212:215], v[106:109]
	v_mfma_f32_16x16x32_bf16 v[90:93], v[174:177], v[220:223], v[90:93]
	v_mfma_f32_16x16x32_bf16 v[90:93], v[178:181], v[224:227], v[90:93]
	v_mfma_f32_16x16x32_bf16 v[46:49], v[182:185], v[190:193], v[46:49]
	v_mfma_f32_16x16x32_bf16 v[46:49], v[186:189], v[196:199], v[46:49]
	v_mfma_f32_16x16x32_bf16 v[118:121], v[182:185], v[200:203], v[118:121]
	v_mfma_f32_16x16x32_bf16 v[118:121], v[186:189], v[204:207], v[118:121]
	v_mfma_f32_16x16x32_bf16 v[102:105], v[182:185], v[208:211], v[102:105]
	v_mfma_f32_16x16x32_bf16 v[102:105], v[186:189], v[212:215], v[102:105]
	v_mfma_f32_16x16x32_bf16 v[86:89], v[182:185], v[220:223], v[86:89]
	v_mfma_f32_16x16x32_bf16 v[86:89], v[186:189], v[224:227], v[86:89]
	s_setprio 0
	s_waitcnt vmcnt(8)
	s_barrier
	ds_read_b128 v[190:193], v171 offset:16384
	ds_read_b128 v[196:199], v171 offset:17408
	ds_read_b128 v[200:203], v171 offset:18432
	ds_read_b128 v[204:207], v171 offset:19456
	ds_read_b128 v[208:211], v171 offset:20480
	ds_read_b128 v[212:215], v171 offset:21504
	ds_read_b128 v[220:223], v171 offset:22528
	ds_read_b128 v[224:227], v171 offset:23552
	s_add_u32 vcc_lo, s90, 0x100000
	s_addc_u32 vcc_hi, s91, 0
	s_add_i32 m0, s27, 0x10000
	s_nop 0
	global_load_lds_dwordx4 v136, s[90:91]
	s_add_i32 m0, s27, 0x12000
	s_nop 0
	global_load_lds_dwordx4 v140, s[90:91]
	s_add_i32 m0, s27, 0x14000
	s_nop 0
	global_load_lds_dwordx4 v136, vcc
	s_add_i32 m0, s27, 0x16000
	s_nop 0
	global_load_lds_dwordx4 v140, vcc
	s_waitcnt lgkmcnt(0)
	s_setprio 1
	v_mfma_f32_16x16x32_bf16 v[82:85], v[150:153], v[190:193], v[82:85]
	v_mfma_f32_16x16x32_bf16 v[82:85], v[154:157], v[196:199], v[82:85]
	v_mfma_f32_16x16x32_bf16 v[66:69], v[150:153], v[200:203], v[66:69]
	v_mfma_f32_16x16x32_bf16 v[66:69], v[154:157], v[204:207], v[66:69]
	v_mfma_f32_16x16x32_bf16 v[42:45], v[150:153], v[208:211], v[42:45]
	v_mfma_f32_16x16x32_bf16 v[42:45], v[154:157], v[212:215], v[42:45]
	v_mfma_f32_16x16x32_bf16 v[18:21], v[150:153], v[220:223], v[18:21]
	v_mfma_f32_16x16x32_bf16 v[18:21], v[154:157], v[224:227], v[18:21]
	v_mfma_f32_16x16x32_bf16 v[78:81], v[158:161], v[190:193], v[78:81]
	v_mfma_f32_16x16x32_bf16 v[78:81], v[162:165], v[196:199], v[78:81]
	v_mfma_f32_16x16x32_bf16 v[62:65], v[158:161], v[200:203], v[62:65]
	v_mfma_f32_16x16x32_bf16 v[62:65], v[162:165], v[204:207], v[62:65]
	v_mfma_f32_16x16x32_bf16 v[34:37], v[158:161], v[208:211], v[34:37]
	v_mfma_f32_16x16x32_bf16 v[34:37], v[162:165], v[212:215], v[34:37]
	v_mfma_f32_16x16x32_bf16 v[14:17], v[158:161], v[220:223], v[14:17]
	v_mfma_f32_16x16x32_bf16 v[14:17], v[162:165], v[224:227], v[14:17]
	v_mfma_f32_16x16x32_bf16 v[74:77], v[174:177], v[190:193], v[74:77]
	v_mfma_f32_16x16x32_bf16 v[74:77], v[178:181], v[196:199], v[74:77]
	v_mfma_f32_16x16x32_bf16 v[58:61], v[174:177], v[200:203], v[58:61]
	v_mfma_f32_16x16x32_bf16 v[58:61], v[178:181], v[204:207], v[58:61]
	v_mfma_f32_16x16x32_bf16 v[26:29], v[174:177], v[208:211], v[26:29]
	v_mfma_f32_16x16x32_bf16 v[26:29], v[178:181], v[212:215], v[26:29]
	v_mfma_f32_16x16x32_bf16 v[10:13], v[174:177], v[220:223], v[10:13]
	v_mfma_f32_16x16x32_bf16 v[10:13], v[178:181], v[224:227], v[10:13]
	v_mfma_f32_16x16x32_bf16 v[70:73], v[182:185], v[190:193], v[70:73]
	v_mfma_f32_16x16x32_bf16 v[70:73], v[186:189], v[196:199], v[70:73]
	v_mfma_f32_16x16x32_bf16 v[54:57], v[182:185], v[200:203], v[54:57]
	v_mfma_f32_16x16x32_bf16 v[54:57], v[186:189], v[204:207], v[54:57]
	v_mfma_f32_16x16x32_bf16 v[22:25], v[182:185], v[208:211], v[22:25]
	v_mfma_f32_16x16x32_bf16 v[22:25], v[186:189], v[212:215], v[22:25]
	v_mfma_f32_16x16x32_bf16 v[4:7], v[182:185], v[220:223], v[6:9]
	v_mfma_f32_16x16x32_bf16 v[4:7], v[186:189], v[224:227], v[4:7]
	s_setprio 0
	s_waitcnt vmcnt(6)
	s_barrier
; #define PG8_BAR __builtin_amdgcn_s_barrier()
; template <class Epi, class Sched, bool ALIGN_EPI = false, bool SP2 = false>
; __device__ __forceinline__ void gemm_phase(PG8_LAS unsigned char* lds, const Gemm g, const Sched& S, const Epi& E) {
;     ...
;     Unit cur, nxt; int ui = 0;
;     if (!S.next(0, cur)) return;
;     f32x4 acc[2][2][4][2];
; #pragma unroll
;     for (int a = 0; a < 2; ++a)
; #pragma unroll
;         for (int b = 0; b < 2; ++b)
; #pragma unroll
;             for (int m = 0; m < 4; ++m)
; #pragma unroll
;                 for (int n = 0; n < 2; ++n) acc[a][b][m][n] = (f32x4){0.f, 0.f, 0.f, 0.f};
;     bf16x8 At[4][2], B0[2][2], B1[2][2];
;     const char* cA; const char* cB; S.bases(cur, g, tstep, cA, cB);
;     S.a_ready(cur);
;     if constexpr (SP2) {
;         PG8_STAGE(PG8_SB(0, 0), cB, voffB); PG8_STAGE(PG8_SB(0, 1), cB + hstep, voffB); PG8_STAGE(PG8_SA(0, 0), cA, voffA); PG8_STAGE(PG8_SA(0, 1), cA + hstep, voffA);
;         if (wr == 1) PG8_BAR;
;         PG8_WAIT_V(2); PG8_BAR;
;         PG8_STAGE(PG8_SB(1, 0), cB + kstep, voffB); PG8_STAGE(PG8_SA(1, 0), cA + kstep, voffA); PG8_STAGE(PG8_SB(1, 1), cB + hstep + kstep, voffB);
;         PG8_WAIT_V(6); PG8_BAR;
;     } else {
;         PG8_STAGE(PG8_SB(0, 0), cB, voffB); PG8_STAGE(PG8_SA(0, 0), cA, voffA); PG8_STAGE(PG8_SB(0, 1), cB + hstep, voffB); PG8_STAGE(PG8_SA(0, 1), cA + hstep, voffA);
;         if (wr == 1) PG8_BAR;
;         PG8_WAIT_V(4); PG8_BAR;
;         PG8_STAGE(PG8_SB(1, 0), cB + kstep, voffB); PG8_STAGE(PG8_SA(1, 0), cA + kstep, voffA); PG8_STAGE(PG8_SB(1, 1), cB + hstep + kstep, voffB);
;         PG8_WAIT_V(6); PG8_BAR;
;     }
;     for (;;) {
;         const bool has_next = S.next(ui + 1, nxt);
;         const char* nA = cA; const char* nB = cB; if (has_next) S.bases(nxt, g, tstep, nA, nB);
;         for (int t = 0; t < nt; t += 2) {
;             const bool last = (t == nt - 2);
;             const char* a1 = cA + (size_t)(t + 1) * kstep;
;             const char* a2 = last ? nA : cA + (size_t)(t + 2) * kstep; const char* b2 = last ? nB : cB + (size_t)(t + 2) * kstep;
;             const char* a3 = a2 + kstep; const char* b3 = b2 + kstep;
;             if (last && has_next) S.a_ready(nxt);
;             if constexpr (Epi::MIDK) { if (t == (nt >> 1)) { E.midk(acc, wr, fr); asm volatile("s_waitcnt lgkmcnt(0)" ::: "memory"); } }
;             if constexpr (SP2) {
	s_add_i32 s0, 0, 0x18000
	v_add_u32_e32 v3, s0, v167
	s_add_i32 s1, 0, 0x1c000
	ds_read_b128 v[150:153], v3
	ds_read_b128 v[154:157], v3 offset:1024
	ds_read_b128 v[158:161], v3 offset:2048
	ds_read_b128 v[162:165], v3 offset:3072
	v_add_u32_e32 v3, s1, v167
	ds_read_b128 v[174:177], v3
	ds_read_b128 v[178:181], v3 offset:1024
	ds_read_b128 v[182:185], v3 offset:2048
	ds_read_b128 v[186:189], v3 offset:3072
	ds_read_b128 v[190:193], v171 offset:32768
	ds_read_b128 v[196:199], v171 offset:33792
	ds_read_b128 v[200:203], v171 offset:34816
	ds_read_b128 v[204:207], v171 offset:35840
	ds_read_b128 v[208:211], v171 offset:36864
	ds_read_b128 v[212:215], v171 offset:37888
	ds_read_b128 v[220:223], v171 offset:38912
	ds_read_b128 v[224:227], v171 offset:39936
	s_add_u32 vcc_lo, s92, 0x100000
	s_addc_u32 vcc_hi, s93, 0
	s_mov_b32 m0, s27
	s_nop 0
	global_load_lds_dwordx4 v134, s[92:93]
	s_add_i32 m0, s27, 0x2000
	s_nop 0
	global_load_lds_dwordx4 v138, s[92:93]
	s_add_i32 m0, s27, 0x4000
	s_nop 0
	global_load_lds_dwordx4 v134, vcc
	s_add_i32 m0, s27, 0x6000
	s_nop 0
	global_load_lds_dwordx4 v138, vcc
	s_waitcnt lgkmcnt(0)
	s_setprio 1
	v_mfma_f32_16x16x32_bf16 v[38:41], v[150:153], v[190:193], v[38:41]
	v_mfma_f32_16x16x32_bf16 v[38:41], v[154:157], v[196:199], v[38:41]
	v_mfma_f32_16x16x32_bf16 v[130:133], v[150:153], v[200:203], v[130:133]
	v_mfma_f32_16x16x32_bf16 v[130:133], v[154:157], v[204:207], v[130:133]
	v_mfma_f32_16x16x32_bf16 v[114:117], v[150:153], v[208:211], v[114:117]
	v_mfma_f32_16x16x32_bf16 v[114:117], v[154:157], v[212:215], v[114:117]
	v_mfma_f32_16x16x32_bf16 v[98:101], v[150:153], v[220:223], v[98:101]
	v_mfma_f32_16x16x32_bf16 v[98:101], v[154:157], v[224:227], v[98:101]
	v_mfma_f32_16x16x32_bf16 v[30:33], v[158:161], v[190:193], v[30:33]
	v_mfma_f32_16x16x32_bf16 v[30:33], v[162:165], v[196:199], v[30:33]
	v_mfma_f32_16x16x32_bf16 v[126:129], v[158:161], v[200:203], v[126:129]
	v_mfma_f32_16x16x32_bf16 v[126:129], v[162:165], v[204:207], v[126:129]
	v_mfma_f32_16x16x32_bf16 v[110:113], v[158:161], v[208:211], v[110:113]
	v_mfma_f32_16x16x32_bf16 v[110:113], v[162:165], v[212:215], v[110:113]
	v_mfma_f32_16x16x32_bf16 v[94:97], v[158:161], v[220:223], v[94:97]
	v_mfma_f32_16x16x32_bf16 v[94:97], v[162:165], v[224:227], v[94:97]
	v_mfma_f32_16x16x32_bf16 v[50:53], v[174:177], v[190:193], v[50:53]
	v_mfma_f32_16x16x32_bf16 v[50:53], v[178:181], v[196:199], v[50:53]
	v_mfma_f32_16x16x32_bf16 v[122:125], v[174:177], v[200:203], v[122:125]
	v_mfma_f32_16x16x32_bf16 v[122:125], v[178:181], v[204:207], v[122:125]
	v_mfma_f32_16x16x32_bf16 v[106:109], v[174:177], v[208:211], v[106:109]
	v_mfma_f32_16x16x32_bf16 v[106:109], v[178:181], v[212:215], v[106:109]
	v_mfma_f32_16x16x32_bf16 v[90:93], v[174:177], v[220:223], v[90:93]
	v_mfma_f32_16x16x32_bf16 v[90:93], v[178:181], v[224:227], v[90:93]
	v_mfma_f32_16x16x32_bf16 v[46:49], v[182:185], v[190:193], v[46:49]
	v_mfma_f32_16x16x32_bf16 v[46:49], v[186:189], v[196:199], v[46:49]
	v_mfma_f32_16x16x32_bf16 v[118:121], v[182:185], v[200:203], v[118:121]
	v_mfma_f32_16x16x32_bf16 v[118:121], v[186:189], v[204:207], v[118:121]
	v_mfma_f32_16x16x32_bf16 v[102:105], v[182:185], v[208:211], v[102:105]
	v_mfma_f32_16x16x32_bf16 v[102:105], v[186:189], v[212:215], v[102:105]
	v_mfma_f32_16x16x32_bf16 v[86:89], v[182:185], v[220:223], v[86:89]
	v_mfma_f32_16x16x32_bf16 v[86:89], v[186:189], v[224:227], v[86:89]
	s_setprio 0
	s_waitcnt vmcnt(8)
	s_barrier
	ds_read_b128 v[190:193], v171 offset:49152
	ds_read_b128 v[196:199], v171 offset:50176
	ds_read_b128 v[200:203], v171 offset:51200
	ds_read_b128 v[204:207], v171 offset:52224
	ds_read_b128 v[208:211], v171 offset:53248
	ds_read_b128 v[212:215], v171 offset:54272
	ds_read_b128 v[220:223], v171 offset:55296
	ds_read_b128 v[224:227], v171 offset:56320
	s_add_u32 s0, s90, 0x80
	s_addc_u32 s1, s91, 0
	s_add_u32 vcc_lo, s0, 0x100000
	s_addc_u32 vcc_hi, s1, 0
	s_add_i32 m0, s27, 0x18000
	s_nop 0
	global_load_lds_dwordx4 v136, s[0:1]
	s_add_i32 m0, s27, 0x1a000
	s_nop 0
	global_load_lds_dwordx4 v140, s[0:1]
	s_add_i32 m0, s27, 0x1c000
	s_nop 0
	global_load_lds_dwordx4 v136, vcc
	s_add_i32 m0, s27, 0x1e000
	s_nop 0
	global_load_lds_dwordx4 v140, vcc
	s_waitcnt lgkmcnt(0)
	s_setprio 1
	v_mfma_f32_16x16x32_bf16 v[82:85], v[150:153], v[190:193], v[82:85]
	v_mfma_f32_16x16x32_bf16 v[82:85], v[154:157], v[196:199], v[82:85]
	v_mfma_f32_16x16x32_bf16 v[66:69], v[150:153], v[200:203], v[66:69]
	v_mfma_f32_16x16x32_bf16 v[66:69], v[154:157], v[204:207], v[66:69]
	v_mfma_f32_16x16x32_bf16 v[42:45], v[150:153], v[208:211], v[42:45]
	v_mfma_f32_16x16x32_bf16 v[42:45], v[154:157], v[212:215], v[42:45]
	v_mfma_f32_16x16x32_bf16 v[18:21], v[150:153], v[220:223], v[18:21]
	v_mfma_f32_16x16x32_bf16 v[18:21], v[154:157], v[224:227], v[18:21]
	v_mfma_f32_16x16x32_bf16 v[78:81], v[158:161], v[190:193], v[78:81]
	v_mfma_f32_16x16x32_bf16 v[78:81], v[162:165], v[196:199], v[78:81]
	v_mfma_f32_16x16x32_bf16 v[62:65], v[158:161], v[200:203], v[62:65]
	v_mfma_f32_16x16x32_bf16 v[62:65], v[162:165], v[204:207], v[62:65]
	v_mfma_f32_16x16x32_bf16 v[34:37], v[158:161], v[208:211], v[34:37]
	v_mfma_f32_16x16x32_bf16 v[34:37], v[162:165], v[212:215], v[34:37]
	v_mfma_f32_16x16x32_bf16 v[14:17], v[158:161], v[220:223], v[14:17]
	v_mfma_f32_16x16x32_bf16 v[14:17], v[162:165], v[224:227], v[14:17]
	v_mfma_f32_16x16x32_bf16 v[74:77], v[174:177], v[190:193], v[74:77]
	v_mfma_f32_16x16x32_bf16 v[74:77], v[178:181], v[196:199], v[74:77]
	v_mfma_f32_16x16x32_bf16 v[58:61], v[174:177], v[200:203], v[58:61]
	v_mfma_f32_16x16x32_bf16 v[58:61], v[178:181], v[204:207], v[58:61]
	v_mfma_f32_16x16x32_bf16 v[26:29], v[174:177], v[208:211], v[26:29]
	v_mfma_f32_16x16x32_bf16 v[26:29], v[178:181], v[212:215], v[26:29]
	v_mfma_f32_16x16x32_bf16 v[8:11], v[174:177], v[220:223], v[10:13]
	v_mfma_f32_16x16x32_bf16 v[10:13], v[178:181], v[224:227], v[8:11]
	v_mfma_f32_16x16x32_bf16 v[70:73], v[182:185], v[190:193], v[70:73]
	v_mfma_f32_16x16x32_bf16 v[70:73], v[186:189], v[196:199], v[70:73]
	v_mfma_f32_16x16x32_bf16 v[54:57], v[182:185], v[200:203], v[54:57]
	v_mfma_f32_16x16x32_bf16 v[54:57], v[186:189], v[204:207], v[54:57]
	v_mfma_f32_16x16x32_bf16 v[22:25], v[182:185], v[208:211], v[22:25]
	v_mfma_f32_16x16x32_bf16 v[22:25], v[186:189], v[212:215], v[22:25]
	v_mfma_f32_16x16x32_bf16 v[4:7], v[182:185], v[220:223], v[4:7]
	v_mfma_f32_16x16x32_bf16 v[6:9], v[186:189], v[224:227], v[4:7]
	s_setprio 0
	s_waitcnt vmcnt(6)
	s_barrier
	s_add_i32 s23, s23, 2
	s_add_u32 s88, s88, 0x100
	s_addc_u32 s89, s89, 0
	s_add_u32 s9, s9, 0x100
	s_addc_u32 s21, s21, 0
	s_cmp_gt_u32 s23, 61
	s_cbranch_scc0 .LBB0_349
	s_branch .Lip_exit
; #define PG8_BAR __builtin_amdgcn_s_barrier()
; template <class Epi, class Sched, bool ALIGN_EPI = false, bool SP2 = false>
; __device__ __forceinline__ void gemm_phase(PG8_LAS unsigned char* lds, const Gemm g, const Sched& S, const Epi& E) {
;     ...
;     Unit cur, nxt; int ui = 0;
;     if (!S.next(0, cur)) return;
;     f32x4 acc[2][2][4][2];
; #pragma unroll
;     for (int a = 0; a < 2; ++a)
; #pragma unroll
;         for (int b = 0; b < 2; ++b)
; #pragma unroll
;             for (int m = 0; m < 4; ++m)
; #pragma unroll
;                 for (int n = 0; n < 2; ++n) acc[a][b][m][n] = (f32x4){0.f, 0.f, 0.f, 0.f};
;     bf16x8 At[4][2], B0[2][2], B1[2][2];
;     const char* cA; const char* cB; S.bases(cur, g, tstep, cA, cB);
;     S.a_ready(cur);
;     if constexpr (SP2) {
;         PG8_STAGE(PG8_SB(0, 0), cB, voffB); PG8_STAGE(PG8_SB(0, 1), cB + hstep, voffB); PG8_STAGE(PG8_SA(0, 0), cA, voffA); PG8_STAGE(PG8_SA(0, 1), cA + hstep, voffA);
;         if (wr == 1) PG8_BAR;
;         PG8_WAIT_V(2); PG8_BAR;
;         PG8_STAGE(PG8_SB(1, 0), cB + kstep, voffB); PG8_STAGE(PG8_SA(1, 0), cA + kstep, voffA); PG8_STAGE(PG8_SB(1, 1), cB + hstep + kstep, voffB);
;         PG8_WAIT_V(6); PG8_BAR;
;     } else {
;         PG8_STAGE(PG8_SB(0, 0), cB, voffB); PG8_STAGE(PG8_SA(0, 0), cA, voffA); PG8_STAGE(PG8_SB(0, 1), cB + hstep, voffB); PG8_STAGE(PG8_SA(0, 1), cA + hstep, voffA);
;         if (wr == 1) PG8_BAR;
;         PG8_WAIT_V(4); PG8_BAR;
;         PG8_STAGE(PG8_SB(1, 0), cB + kstep, voffB); PG8_STAGE(PG8_SA(1, 0), cA + kstep, voffA); PG8_STAGE(PG8_SB(1, 1), cB + hstep + kstep, voffB);
;         PG8_WAIT_V(6); PG8_BAR;
;     }
;     for (;;) {
;         const bool has_next = S.next(ui + 1, nxt);
;         const char* nA = cA; const char* nB = cB; if (has_next) S.bases(nxt, g, tstep, nA, nB);
;         for (int t = 0; t < nt; t += 2) {
;             const bool last = (t == nt - 2);
;             const char* a1 = cA + (size_t)(t + 1) * kstep;
;             const char* a2 = last ? nA : cA + (size_t)(t + 2) * kstep; const char* b2 = last ? nB : cB + (size_t)(t + 2) * kstep;
;             const char* a3 = a2 + kstep; const char* b3 = b2 + kstep;
;             if (last && has_next) S.a_ready(nxt);
;             if constexpr (Epi::MIDK) { if (t == (nt >> 1)) { E.midk(acc, wr, fr); asm volatile("s_waitcnt lgkmcnt(0)" ::: "memory"); } }
;             if constexpr (SP2) {
.Lip_h1:
	ds_read_b128 v[150:153], v169
	ds_read_b128 v[154:157], v169 offset:1024
	ds_read_b128 v[158:161], v169 offset:2048
	ds_read_b128 v[162:165], v169 offset:3072
	ds_read_b128 v[174:177], v170
	ds_read_b128 v[178:181], v170 offset:1024
	ds_read_b128 v[182:185], v170 offset:2048
	ds_read_b128 v[186:189], v170 offset:3072
	s_add_u32 s0, s88, 0xfff00080
	s_addc_u32 s1, s89, -1
	s_cmp_eq_u32 s23, 60
	s_cselect_b32 s93, s51, s1
	s_cselect_b32 s92, s50, s0
	s_cselect_b32 s91, s53, s21
	s_cselect_b32 s90, s52, s9
	ds_read_b128 v[190:193], v171
	ds_read_b128 v[196:199], v171 offset:1024
	ds_read_b128 v[200:203], v171 offset:2048
	ds_read_b128 v[204:207], v171 offset:3072
	ds_read_b128 v[208:211], v171 offset:4096
	ds_read_b128 v[212:215], v171 offset:5120
	ds_read_b128 v[220:223], v171 offset:6144
	ds_read_b128 v[224:227], v171 offset:7168
	s_add_u32 s0, s88, 0xfff00000
	s_addc_u32 s1, s89, -1
	s_add_i32 m0, s27, 0x8000
	s_nop 0
	global_load_lds_dwordx4 v134, s[0:1]
	s_add_i32 m0, s27, 0xa000
	s_nop 0
	global_load_lds_dwordx4 v138, s[0:1]
	s_add_i32 m0, s27, 0xc000
	s_nop 0
	global_load_lds_dwordx4 v134, s[88:89]
	s_add_i32 m0, s27, 0xe000
	s_nop 0
	global_load_lds_dwordx4 v138, s[88:89]
	s_sleep 2
	s_waitcnt lgkmcnt(0)
	s_waitcnt vmcnt(8)
	s_barrier
	s_setprio 2
	v_mfma_f32_16x16x32_bf16 v[38:41], v[150:153], v[190:193], v[38:41]
	v_mfma_f32_16x16x32_bf16 v[38:41], v[154:157], v[196:199], v[38:41]
	v_mfma_f32_16x16x32_bf16 v[130:133], v[150:153], v[200:203], v[130:133]
	v_mfma_f32_16x16x32_bf16 v[130:133], v[154:157], v[204:207], v[130:133]
	v_mfma_f32_16x16x32_bf16 v[114:117], v[150:153], v[208:211], v[114:117]
	v_mfma_f32_16x16x32_bf16 v[114:117], v[154:157], v[212:215], v[114:117]
	v_mfma_f32_16x16x32_bf16 v[98:101], v[150:153], v[220:223], v[98:101]
	v_mfma_f32_16x16x32_bf16 v[98:101], v[154:157], v[224:227], v[98:101]
	v_mfma_f32_16x16x32_bf16 v[30:33], v[158:161], v[190:193], v[30:33]
	v_mfma_f32_16x16x32_bf16 v[30:33], v[162:165], v[196:199], v[30:33]
	v_mfma_f32_16x16x32_bf16 v[126:129], v[158:161], v[200:203], v[126:129]
	v_mfma_f32_16x16x32_bf16 v[126:129], v[162:165], v[204:207], v[126:129]
	v_mfma_f32_16x16x32_bf16 v[110:113], v[158:161], v[208:211], v[110:113]
	v_mfma_f32_16x16x32_bf16 v[110:113], v[162:165], v[212:215], v[110:113]
	v_mfma_f32_16x16x32_bf16 v[94:97], v[158:161], v[220:223], v[94:97]
	v_mfma_f32_16x16x32_bf16 v[94:97], v[162:165], v[224:227], v[94:97]
	v_mfma_f32_16x16x32_bf16 v[50:53], v[174:177], v[190:193], v[50:53]
	v_mfma_f32_16x16x32_bf16 v[50:53], v[178:181], v[196:199], v[50:53]
	v_mfma_f32_16x16x32_bf16 v[122:125], v[174:177], v[200:203], v[122:125]
	v_mfma_f32_16x16x32_bf16 v[122:125], v[178:181], v[204:207], v[122:125]
	v_mfma_f32_16x16x32_bf16 v[106:109], v[174:177], v[208:211], v[106:109]
	v_mfma_f32_16x16x32_bf16 v[106:109], v[178:181], v[212:215], v[106:109]
	v_mfma_f32_16x16x32_bf16 v[90:93], v[174:177], v[220:223], v[90:93]
	v_mfma_f32_16x16x32_bf16 v[90:93], v[178:181], v[224:227], v[90:93]
	v_mfma_f32_16x16x32_bf16 v[46:49], v[182:185], v[190:193], v[46:49]
	v_mfma_f32_16x16x32_bf16 v[46:49], v[186:189], v[196:199], v[46:49]
	v_mfma_f32_16x16x32_bf16 v[118:121], v[182:185], v[200:203], v[118:121]
	v_mfma_f32_16x16x32_bf16 v[118:121], v[186:189], v[204:207], v[118:121]
	v_mfma_f32_16x16x32_bf16 v[102:105], v[182:185], v[208:211], v[102:105]
	v_mfma_f32_16x16x32_bf16 v[102:105], v[186:189], v[212:215], v[102:105]
	v_mfma_f32_16x16x32_bf16 v[86:89], v[182:185], v[220:223], v[86:89]
	v_mfma_f32_16x16x32_bf16 v[86:89], v[186:189], v[224:227], v[86:89]
	s_setprio 0
	ds_read_b128 v[190:193], v171 offset:16384
	ds_read_b128 v[196:199], v171 offset:17408
	ds_read_b128 v[200:203], v171 offset:18432
	ds_read_b128 v[204:207], v171 offset:19456
	ds_read_b128 v[208:211], v171 offset:20480
	ds_read_b128 v[212:215], v171 offset:21504
	ds_read_b128 v[220:223], v171 offset:22528
	ds_read_b128 v[224:227], v171 offset:23552
	s_add_u32 vcc_lo, s90, 0x100000
	s_addc_u32 vcc_hi, s91, 0
	s_add_i32 m0, s27, 0x10000
	s_nop 0
	global_load_lds_dwordx4 v136, s[90:91]
	s_add_i32 m0, s27, 0x12000
	s_nop 0
	global_load_lds_dwordx4 v140, s[90:91]
	s_add_i32 m0, s27, 0x14000
	s_nop 0
	global_load_lds_dwordx4 v136, vcc
	s_add_i32 m0, s27, 0x16000
	s_nop 0
	global_load_lds_dwordx4 v140, vcc
	s_sleep 2
	s_waitcnt lgkmcnt(0)
	s_waitcnt vmcnt(6)
	s_barrier
; #define PG8_BAR __builtin_amdgcn_s_barrier()
; template <class Epi, class Sched, bool ALIGN_EPI = false, bool SP2 = false>
; __device__ __forceinline__ void gemm_phase(PG8_LAS unsigned char* lds, const Gemm g, const Sched& S, const Epi& E) {
;     ...
;     Unit cur, nxt; int ui = 0;
;     if (!S.next(0, cur)) return;
;     f32x4 acc[2][2][4][2];
; #pragma unroll
;     for (int a = 0; a < 2; ++a)
; #pragma unroll
;         for (int b = 0; b < 2; ++b)
; #pragma unroll
;             for (int m = 0; m < 4; ++m)
; #pragma unroll
;                 for (int n = 0; n < 2; ++n) acc[a][b][m][n] = (f32x4){0.f, 0.f, 0.f, 0.f};
;     bf16x8 At[4][2], B0[2][2], B1[2][2];
;     const char* cA; const char* cB; S.bases(cur, g, tstep, cA, cB);
;     S.a_ready(cur);
;     if constexpr (SP2) {
;         PG8_STAGE(PG8_SB(0, 0), cB, voffB); PG8_STAGE(PG8_SB(0, 1), cB + hstep, voffB); PG8_STAGE(PG8_SA(0, 0), cA, voffA); PG8_STAGE(PG8_SA(0, 1), cA + hstep, voffA);
;         if (wr == 1) PG8_BAR;
;         PG8_WAIT_V(2); PG8_BAR;
;         PG8_STAGE(PG8_SB(1, 0), cB + kstep, voffB); PG8_STAGE(PG8_SA(1, 0), cA + kstep, voffA); PG8_STAGE(PG8_SB(1, 1), cB + hstep + kstep, voffB);
;         PG8_WAIT_V(6); PG8_BAR;
;     } else {
;         PG8_STAGE(PG8_SB(0, 0), cB, voffB); PG8_STAGE(PG8_SA(0, 0), cA, voffA); PG8_STAGE(PG8_SB(0, 1), cB + hstep, voffB); PG8_STAGE(PG8_SA(0, 1), cA + hstep, voffA);
;         if (wr == 1) PG8_BAR;
;         PG8_WAIT_V(4); PG8_BAR;
;         PG8_STAGE(PG8_SB(1, 0), cB + kstep, voffB); PG8_STAGE(PG8_SA(1, 0), cA + kstep, voffA); PG8_STAGE(PG8_SB(1, 1), cB + hstep + kstep, voffB);
;         PG8_WAIT_V(6); PG8_BAR;
;     }
;     for (;;) {
;         const bool has_next = S.next(ui + 1, nxt);
;         const char* nA = cA; const char* nB = cB; if (has_next) S.bases(nxt, g, tstep, nA, nB);
;         for (int t = 0; t < nt; t += 2) {
;             const bool last = (t == nt - 2);
;             const char* a1 = cA + (size_t)(t + 1) * kstep;
;             const char* a2 = last ? nA : cA + (size_t)(t + 2) * kstep; const char* b2 = last ? nB : cB + (size_t)(t + 2) * kstep;
;             const char* a3 = a2 + kstep; const char* b3 = b2 + kstep;
;             if (last && has_next) S.a_ready(nxt);
;             if constexpr (Epi::MIDK) { if (t == (nt >> 1)) { E.midk(acc, wr, fr); asm volatile("s_waitcnt lgkmcnt(0)" ::: "memory"); } }
;             if constexpr (SP2) {
	s_setprio 2
	v_mfma_f32_16x16x32_bf16 v[82:85], v[150:153], v[190:193], v[82:85]
	v_mfma_f32_16x16x32_bf16 v[82:85], v[154:157], v[196:199], v[82:85]
	v_mfma_f32_16x16x32_bf16 v[66:69], v[150:153], v[200:203], v[66:69]
	v_mfma_f32_16x16x32_bf16 v[66:69], v[154:157], v[204:207], v[66:69]
	v_mfma_f32_16x16x32_bf16 v[42:45], v[150:153], v[208:211], v[42:45]
	v_mfma_f32_16x16x32_bf16 v[42:45], v[154:157], v[212:215], v[42:45]
	v_mfma_f32_16x16x32_bf16 v[18:21], v[150:153], v[220:223], v[18:21]
	v_mfma_f32_16x16x32_bf16 v[18:21], v[154:157], v[224:227], v[18:21]
	v_mfma_f32_16x16x32_bf16 v[78:81], v[158:161], v[190:193], v[78:81]
	v_mfma_f32_16x16x32_bf16 v[78:81], v[162:165], v[196:199], v[78:81]
	v_mfma_f32_16x16x32_bf16 v[62:65], v[158:161], v[200:203], v[62:65]
	v_mfma_f32_16x16x32_bf16 v[62:65], v[162:165], v[204:207], v[62:65]
	v_mfma_f32_16x16x32_bf16 v[34:37], v[158:161], v[208:211], v[34:37]
	v_mfma_f32_16x16x32_bf16 v[34:37], v[162:165], v[212:215], v[34:37]
	v_mfma_f32_16x16x32_bf16 v[14:17], v[158:161], v[220:223], v[14:17]
	v_mfma_f32_16x16x32_bf16 v[14:17], v[162:165], v[224:227], v[14:17]
	v_mfma_f32_16x16x32_bf16 v[74:77], v[174:177], v[190:193], v[74:77]
	v_mfma_f32_16x16x32_bf16 v[74:77], v[178:181], v[196:199], v[74:77]
	v_mfma_f32_16x16x32_bf16 v[58:61], v[174:177], v[200:203], v[58:61]
	v_mfma_f32_16x16x32_bf16 v[58:61], v[178:181], v[204:207], v[58:61]
	v_mfma_f32_16x16x32_bf16 v[26:29], v[174:177], v[208:211], v[26:29]
	v_mfma_f32_16x16x32_bf16 v[26:29], v[178:181], v[212:215], v[26:29]
	v_mfma_f32_16x16x32_bf16 v[10:13], v[174:177], v[220:223], v[10:13]
	v_mfma_f32_16x16x32_bf16 v[10:13], v[178:181], v[224:227], v[10:13]
	v_mfma_f32_16x16x32_bf16 v[70:73], v[182:185], v[190:193], v[70:73]
	v_mfma_f32_16x16x32_bf16 v[70:73], v[186:189], v[196:199], v[70:73]
	v_mfma_f32_16x16x32_bf16 v[54:57], v[182:185], v[200:203], v[54:57]
	v_mfma_f32_16x16x32_bf16 v[54:57], v[186:189], v[204:207], v[54:57]
	v_mfma_f32_16x16x32_bf16 v[22:25], v[182:185], v[208:211], v[22:25]
	v_mfma_f32_16x16x32_bf16 v[22:25], v[186:189], v[212:215], v[22:25]
	v_mfma_f32_16x16x32_bf16 v[4:7], v[182:185], v[220:223], v[6:9]
	v_mfma_f32_16x16x32_bf16 v[4:7], v[186:189], v[224:227], v[4:7]
	s_setprio 0
	s_add_i32 s0, 0, 0x18000
	v_add_u32_e32 v3, s0, v167
	s_add_i32 s1, 0, 0x1c000
	ds_read_b128 v[150:153], v3
	ds_read_b128 v[154:157], v3 offset:1024
	ds_read_b128 v[158:161], v3 offset:2048
	ds_read_b128 v[162:165], v3 offset:3072
	v_add_u32_e32 v3, s1, v167
	ds_read_b128 v[174:177], v3
	ds_read_b128 v[178:181], v3 offset:1024
	ds_read_b128 v[182:185], v3 offset:2048
	ds_read_b128 v[186:189], v3 offset:3072
	ds_read_b128 v[190:193], v171 offset:32768
	ds_read_b128 v[196:199], v171 offset:33792
	ds_read_b128 v[200:203], v171 offset:34816
	ds_read_b128 v[204:207], v171 offset:35840
	ds_read_b128 v[208:211], v171 offset:36864
	ds_read_b128 v[212:215], v171 offset:37888
	ds_read_b128 v[220:223], v171 offset:38912
	ds_read_b128 v[224:227], v171 offset:39936
	s_add_u32 vcc_lo, s92, 0x100000
	s_addc_u32 vcc_hi, s93, 0
	s_mov_b32 m0, s27
	s_nop 0
	global_load_lds_dwordx4 v134, s[92:93]
	s_add_i32 m0, s27, 0x2000
	s_nop 0
	global_load_lds_dwordx4 v138, s[92:93]
	s_add_i32 m0, s27, 0x4000
	s_nop 0
	global_load_lds_dwordx4 v134, vcc
	s_add_i32 m0, s27, 0x6000
	s_nop 0
	global_load_lds_dwordx4 v138, vcc
	s_sleep 2
	s_waitcnt lgkmcnt(0)
	s_waitcnt vmcnt(8)
	s_barrier
; #define PG8_STAGE(bufoff, gbase, voff) do { _Pragma("unroll") for (int _i = 0; _i < 2; ++_i) \
;         __builtin_amdgcn_global_load_lds((const unsigned*)((const char*)(gbase) + (voff)[_i]), (PG8_LAS unsigned*)(lds + (bufoff) + ldsw + _i * 8192), 16, 0, 0); } while (0)
; #define PG8_LDA(dst, b, h) do { _Pragma("unroll") for (int m = 0; m < 4; ++m) _Pragma("unroll") for (int k = 0; k < 2; ++k) dst[m][k] = *(const PG8_LAS bf16x8*)(lds + PG8_SA(b, h) + aoff + m * 2048 + k * 1024); } while (0)
; #define PG8_MMA(ai, bj, At, Bt) do { __builtin_amdgcn_s_setprio(1); _Pragma("unroll") for (int m = 0; m < 4; ++m) _Pragma("unroll") for (int n = 0; n < 2; ++n) _Pragma("unroll") for (int k = 0; k < 2; ++k) \
;         acc[ai][bj][m][n] = __builtin_amdgcn_mfma_f32_16x16x32_bf16(Bt[n][k], At[m][k], acc[ai][bj][m][n], 0, 0, 0); __builtin_amdgcn_s_setprio(0); } while (0)
; #define PG8_WAIT_V(n) asm volatile("s_waitcnt vmcnt(" #n ")" ::: "memory")
; #define PG8_WAIT_L(n) asm volatile("s_waitcnt lgkmcnt(" #n ")" ::: "memory")
; #define PG8_BAR __builtin_amdgcn_s_barrier()
; #define PG8_SCHED __builtin_amdgcn_sched_barrier(0)
; template <class Epi, class Sched, bool ALIGN_EPI = false, bool SP2 = false>
; __device__ __forceinline__ void gemm_phase(PG8_LAS unsigned char* lds, const Gemm g, const Sched& S, const Epi& E) {
;     ...
;             PG8_WAIT_V(8); PG8_WAIT_L(0); PG8_BAR; PG8_MMA(0, 0, At, B0); PG8_MMA(0, 1, At, B1); PG8_BAR; PG8_SCHED;
;             PG8_LDA(At, 1, 1); PG8_STAGE(PG8_SB(1, 0), b3, voffB); PG8_STAGE(PG8_SB(1, 1), b3 + hstep, voffB); PG8_STAGE(PG8_SA(1, 0), a3, voffA);
;             PG8_WAIT_V(8); PG8_WAIT_L(0); PG8_BAR; PG8_MMA(1, 0, At, B0); PG8_MMA(1, 1, At, B1); PG8_BAR; PG8_SCHED;
	s_setprio 2
	v_mfma_f32_16x16x32_bf16 v[38:41], v[150:153], v[190:193], v[38:41]
	v_mfma_f32_16x16x32_bf16 v[38:41], v[154:157], v[196:199], v[38:41]
	v_mfma_f32_16x16x32_bf16 v[130:133], v[150:153], v[200:203], v[130:133]
	v_mfma_f32_16x16x32_bf16 v[130:133], v[154:157], v[204:207], v[130:133]
	v_mfma_f32_16x16x32_bf16 v[114:117], v[150:153], v[208:211], v[114:117]
	v_mfma_f32_16x16x32_bf16 v[114:117], v[154:157], v[212:215], v[114:117]
	v_mfma_f32_16x16x32_bf16 v[98:101], v[150:153], v[220:223], v[98:101]
	v_mfma_f32_16x16x32_bf16 v[98:101], v[154:157], v[224:227], v[98:101]
	v_mfma_f32_16x16x32_bf16 v[30:33], v[158:161], v[190:193], v[30:33]
	v_mfma_f32_16x16x32_bf16 v[30:33], v[162:165], v[196:199], v[30:33]
	v_mfma_f32_16x16x32_bf16 v[126:129], v[158:161], v[200:203], v[126:129]
	v_mfma_f32_16x16x32_bf16 v[126:129], v[162:165], v[204:207], v[126:129]
	v_mfma_f32_16x16x32_bf16 v[110:113], v[158:161], v[208:211], v[110:113]
	v_mfma_f32_16x16x32_bf16 v[110:113], v[162:165], v[212:215], v[110:113]
	v_mfma_f32_16x16x32_bf16 v[94:97], v[158:161], v[220:223], v[94:97]
	v_mfma_f32_16x16x32_bf16 v[94:97], v[162:165], v[224:227], v[94:97]
	v_mfma_f32_16x16x32_bf16 v[50:53], v[174:177], v[190:193], v[50:53]
	v_mfma_f32_16x16x32_bf16 v[50:53], v[178:181], v[196:199], v[50:53]
	v_mfma_f32_16x16x32_bf16 v[122:125], v[174:177], v[200:203], v[122:125]
	v_mfma_f32_16x16x32_bf16 v[122:125], v[178:181], v[204:207], v[122:125]
	v_mfma_f32_16x16x32_bf16 v[106:109], v[174:177], v[208:211], v[106:109]
	v_mfma_f32_16x16x32_bf16 v[106:109], v[178:181], v[212:215], v[106:109]
	v_mfma_f32_16x16x32_bf16 v[90:93], v[174:177], v[220:223], v[90:93]
	v_mfma_f32_16x16x32_bf16 v[90:93], v[178:181], v[224:227], v[90:93]
	v_mfma_f32_16x16x32_bf16 v[46:49], v[182:185], v[190:193], v[46:49]
	v_mfma_f32_16x16x32_bf16 v[46:49], v[186:189], v[196:199], v[46:49]
	v_mfma_f32_16x16x32_bf16 v[118:121], v[182:185], v[200:203], v[118:121]
	v_mfma_f32_16x16x32_bf16 v[118:121], v[186:189], v[204:207], v[118:121]
	v_mfma_f32_16x16x32_bf16 v[102:105], v[182:185], v[208:211], v[102:105]
	v_mfma_f32_16x16x32_bf16 v[102:105], v[186:189], v[212:215], v[102:105]
	v_mfma_f32_16x16x32_bf16 v[86:89], v[182:185], v[220:223], v[86:89]
	v_mfma_f32_16x16x32_bf16 v[86:89], v[186:189], v[224:227], v[86:89]
	s_setprio 0
	ds_read_b128 v[190:193], v171 offset:49152
	ds_read_b128 v[196:199], v171 offset:50176
	ds_read_b128 v[200:203], v171 offset:51200
	ds_read_b128 v[204:207], v171 offset:52224
	ds_read_b128 v[208:211], v171 offset:53248
	ds_read_b128 v[212:215], v171 offset:54272
	ds_read_b128 v[220:223], v171 offset:55296
	ds_read_b128 v[224:227], v171 offset:56320
	s_add_u32 s0, s90, 0x80
	s_addc_u32 s1, s91, 0
	s_add_u32 vcc_lo, s0, 0x100000
	s_addc_u32 vcc_hi, s1, 0
	s_add_i32 m0, s27, 0x18000
	s_nop 0
	global_load_lds_dwordx4 v136, s[0:1]
	s_add_i32 m0, s27, 0x1a000
	s_nop 0
	global_load_lds_dwordx4 v140, s[0:1]
	s_add_i32 m0, s27, 0x1c000
	s_nop 0
	global_load_lds_dwordx4 v136, vcc
	s_add_i32 m0, s27, 0x1e000
	s_nop 0
	global_load_lds_dwordx4 v140, vcc
	s_sleep 2
	s_waitcnt lgkmcnt(0)
	s_waitcnt vmcnt(6)
	s_barrier
	s_setprio 2
	v_mfma_f32_16x16x32_bf16 v[82:85], v[150:153], v[190:193], v[82:85]
	v_mfma_f32_16x16x32_bf16 v[82:85], v[154:157], v[196:199], v[82:85]
	v_mfma_f32_16x16x32_bf16 v[66:69], v[150:153], v[200:203], v[66:69]
	v_mfma_f32_16x16x32_bf16 v[66:69], v[154:157], v[204:207], v[66:69]
	v_mfma_f32_16x16x32_bf16 v[42:45], v[150:153], v[208:211], v[42:45]
	v_mfma_f32_16x16x32_bf16 v[42:45], v[154:157], v[212:215], v[42:45]
	v_mfma_f32_16x16x32_bf16 v[18:21], v[150:153], v[220:223], v[18:21]
	v_mfma_f32_16x16x32_bf16 v[18:21], v[154:157], v[224:227], v[18:21]
	v_mfma_f32_16x16x32_bf16 v[78:81], v[158:161], v[190:193], v[78:81]
	v_mfma_f32_16x16x32_bf16 v[78:81], v[162:165], v[196:199], v[78:81]
	v_mfma_f32_16x16x32_bf16 v[62:65], v[158:161], v[200:203], v[62:65]
	v_mfma_f32_16x16x32_bf16 v[62:65], v[162:165], v[204:207], v[62:65]
	v_mfma_f32_16x16x32_bf16 v[34:37], v[158:161], v[208:211], v[34:37]
	v_mfma_f32_16x16x32_bf16 v[34:37], v[162:165], v[212:215], v[34:37]
	v_mfma_f32_16x16x32_bf16 v[14:17], v[158:161], v[220:223], v[14:17]
	v_mfma_f32_16x16x32_bf16 v[14:17], v[162:165], v[224:227], v[14:17]
	v_mfma_f32_16x16x32_bf16 v[74:77], v[174:177], v[190:193], v[74:77]
	v_mfma_f32_16x16x32_bf16 v[74:77], v[178:181], v[196:199], v[74:77]
	v_mfma_f32_16x16x32_bf16 v[58:61], v[174:177], v[200:203], v[58:61]
	v_mfma_f32_16x16x32_bf16 v[58:61], v[178:181], v[204:207], v[58:61]
	v_mfma_f32_16x16x32_bf16 v[26:29], v[174:177], v[208:211], v[26:29]
	v_mfma_f32_16x16x32_bf16 v[26:29], v[178:181], v[212:215], v[26:29]
	v_mfma_f32_16x16x32_bf16 v[8:11], v[174:177], v[220:223], v[10:13]
	v_mfma_f32_16x16x32_bf16 v[10:13], v[178:181], v[224:227], v[8:11]
	v_mfma_f32_16x16x32_bf16 v[70:73], v[182:185], v[190:193], v[70:73]
	v_mfma_f32_16x16x32_bf16 v[70:73], v[186:189], v[196:199], v[70:73]
	v_mfma_f32_16x16x32_bf16 v[54:57], v[182:185], v[200:203], v[54:57]
	v_mfma_f32_16x16x32_bf16 v[54:57], v[186:189], v[204:207], v[54:57]
	v_mfma_f32_16x16x32_bf16 v[22:25], v[182:185], v[208:211], v[22:25]
	v_mfma_f32_16x16x32_bf16 v[22:25], v[186:189], v[212:215], v[22:25]
	v_mfma_f32_16x16x32_bf16 v[4:7], v[182:185], v[220:223], v[4:7]
	v_mfma_f32_16x16x32_bf16 v[6:9], v[186:189], v[224:227], v[4:7]
	s_setprio 0
	s_add_i32 s23, s23, 2
	s_add_u32 s88, s88, 0x100
	s_addc_u32 s89, s89, 0
	s_add_u32 s9, s9, 0x100
	s_addc_u32 s21, s21, 0
	s_cmp_gt_u32 s23, 61
	s_cbranch_scc0 .Lip_h1

; #define PG8_STAGE(bufoff, gbase, voff) do { _Pragma("unroll") for (int _i = 0; _i < 2; ++_i) \
;         __builtin_amdgcn_global_load_lds((const unsigned*)((const char*)(gbase) + (voff)[_i]), (PG8_LAS unsigned*)(lds + (bufoff) + ldsw + _i * 8192), 16, 0, 0); } while (0)
; #define PG8_LDA(dst, b, h) do { _Pragma("unroll") for (int m = 0; m < 4; ++m) _Pragma("unroll") for (int k = 0; k < 2; ++k) dst[m][k] = *(const PG8_LAS bf16x8*)(lds + PG8_SA(b, h) + aoff + m * 2048 + k * 1024); } while (0)
; #define PG8_LDB(dst, b, h) do { _Pragma("unroll") for (int n = 0; n < 2; ++n) _Pragma("unroll") for (int k = 0; k < 2; ++k) dst[n][k] = *(const PG8_LAS bf16x8*)(lds + PG8_SB(b, h) + boff + n * 2048 + k * 1024); } while (0)
; #define PG8_MMA(ai, bj, At, Bt) do { __builtin_amdgcn_s_setprio(1); _Pragma("unroll") for (int m = 0; m < 4; ++m) _Pragma("unroll") for (int n = 0; n < 2; ++n) _Pragma("unroll") for (int k = 0; k < 2; ++k) \
;         acc[ai][bj][m][n] = __builtin_amdgcn_mfma_f32_16x16x32_bf16(Bt[n][k], At[m][k], acc[ai][bj][m][n], 0, 0, 0); __builtin_amdgcn_s_setprio(0); } while (0)
; #define PG8_BAR __builtin_amdgcn_s_barrier()
; template <class Epi, class Sched, bool ALIGN_EPI = false, bool SP2 = false>
; __device__ __forceinline__ void gemm_phase(PG8_LAS unsigned char* lds, const Gemm g, const Sched& S, const Epi& E) {
;     ...
;             const bool last = (t == nt - 2);
;             const char* a1 = cA + (size_t)(t + 1) * kstep;
;             const char* a2 = last ? nA : cA + (size_t)(t + 2) * kstep; const char* b2 = last ? nB : cB + (size_t)(t + 2) * kstep;
;             const char* a3 = a2 + kstep; const char* b3 = b2 + kstep;
;             if (last && has_next) S.a_ready(nxt);
;             if constexpr (Epi::MIDK) { if (t == (nt >> 1)) { E.midk(acc, wr, fr); asm volatile("s_waitcnt lgkmcnt(0)" ::: "memory"); } }
;             if constexpr (SP2) {
;             PG8_LDB(B0, 0, 0); PG8_LDB(B1, 0, 1); PG8_SCHED; PG8_LDA(At, 0, 0); PG8_STAGE(PG8_SA(1, 1), a1 + hstep, voffA);
;             PG8_WAIT_V(8); PG8_WAIT_L(0); PG8_BAR; PG8_MMA(0, 0, At, B0); PG8_MMA(0, 1, At, B1); PG8_BAR; PG8_SCHED;
;             PG8_LDA(At, 0, 1); PG8_STAGE(PG8_SB(0, 0), b2, voffB); PG8_STAGE(PG8_SB(0, 1), b2 + hstep, voffB); PG8_STAGE(PG8_SA(0, 0), a2, voffA);
;             PG8_WAIT_V(8); PG8_WAIT_L(0); PG8_BAR; PG8_MMA(1, 0, At, B0); PG8_MMA(1, 1, At, B1); PG8_BAR; PG8_SCHED;
.LBB0_911:
	v_add_u32_e32 v3, s83, v219
	ds_read_b128 v[98:101], v3
	ds_read_b128 v[102:105], v3 offset:1024
	ds_read_b128 v[106:109], v3 offset:2048
	ds_read_b128 v[166:169], v3 offset:3072
	v_add_u32_e32 v3, s86, v219
	s_add_u32 s62, s58, s60
	ds_read_b128 v[170:173], v3
	ds_read_b128 v[174:177], v3 offset:1024
	ds_read_b128 v[178:181], v3 offset:2048
	ds_read_b128 v[182:185], v3 offset:3072
	s_addc_u32 s63, s59, s61
	s_add_u32 s62, s62, 0x100
	s_addc_u32 s63, s63, 0
	s_add_u32 s93, s90, s60
	s_addc_u32 s94, s91, s61
	s_cmpk_eq_i32 s60, 0x1f00
	s_cselect_b32 s65, s19, s63
	s_cselect_b32 s64, s21, s62
	s_cselect_b32 s63, s53, s94
	s_cselect_b32 s62, s57, s93
	v_lshl_add_u64 v[4:5], v[94:95], 0, s[60:61]
	s_add_i32 m0, s24, 0xc000
	ds_read_b128 v[186:189], v244
	ds_read_b128 v[190:193], v244 offset:1024
	ds_read_b128 v[196:199], v244 offset:2048
	ds_read_b128 v[200:203], v244 offset:3072
	ds_read_b128 v[204:207], v244 offset:4096
	ds_read_b128 v[208:211], v244 offset:5120
	ds_read_b128 v[212:215], v244 offset:6144
	ds_read_b128 v[246:249], v244 offset:7168
	global_load_lds_dwordx4 v[4:5], off
	v_lshl_add_u64 v[4:5], v[96:97], 0, s[60:61]
	s_add_i32 m0, s24, 0xe000
	s_nop 0
	global_load_lds_dwordx4 v[4:5], off
	s_waitcnt vmcnt(8)
	s_waitcnt lgkmcnt(0)
	s_barrier
	s_setprio 1
	s_waitcnt lgkmcnt(0)
	v_mfma_f32_16x16x32_bf16 v[146:149], v[98:101], v[186:189], v[146:149]
	v_mfma_f32_16x16x32_bf16 v[146:149], v[102:105], v[190:193], v[146:149]
	v_mfma_f32_16x16x32_bf16 v[138:141], v[98:101], v[196:199], v[138:141]
	v_mfma_f32_16x16x32_bf16 v[138:141], v[102:105], v[200:203], v[138:141]
	v_mfma_f32_16x16x32_bf16 v[130:133], v[98:101], v[204:207], v[130:133]
	v_mfma_f32_16x16x32_bf16 v[130:133], v[102:105], v[208:211], v[130:133]
	v_mfma_f32_16x16x32_bf16 v[122:125], v[98:101], v[212:215], v[122:125]
	v_mfma_f32_16x16x32_bf16 v[122:125], v[102:105], v[246:249], v[122:125]
	v_mfma_f32_16x16x32_bf16 v[142:145], v[106:109], v[186:189], v[142:145]
	v_mfma_f32_16x16x32_bf16 v[142:145], v[166:169], v[190:193], v[142:145]
	v_mfma_f32_16x16x32_bf16 v[134:137], v[106:109], v[196:199], v[134:137]
	v_mfma_f32_16x16x32_bf16 v[134:137], v[166:169], v[200:203], v[134:137]
	v_mfma_f32_16x16x32_bf16 v[126:129], v[106:109], v[204:207], v[126:129]
	v_mfma_f32_16x16x32_bf16 v[126:129], v[166:169], v[208:211], v[126:129]
	v_mfma_f32_16x16x32_bf16 v[118:121], v[106:109], v[212:215], v[118:121]
	v_mfma_f32_16x16x32_bf16 v[118:121], v[166:169], v[246:249], v[118:121]
	s_setprio 0
	s_setprio 1
	v_mfma_f32_16x16x32_bf16 v[66:69], v[170:173], v[186:189], v[66:69]
	v_mfma_f32_16x16x32_bf16 v[66:69], v[174:177], v[190:193], v[66:69]
	v_mfma_f32_16x16x32_bf16 v[58:61], v[170:173], v[196:199], v[58:61]
	v_mfma_f32_16x16x32_bf16 v[58:61], v[174:177], v[200:203], v[58:61]
	v_mfma_f32_16x16x32_bf16 v[50:53], v[170:173], v[204:207], v[50:53]
	v_mfma_f32_16x16x32_bf16 v[50:53], v[174:177], v[208:211], v[50:53]
	v_mfma_f32_16x16x32_bf16 v[42:45], v[170:173], v[212:215], v[42:45]
	v_mfma_f32_16x16x32_bf16 v[42:45], v[174:177], v[246:249], v[42:45]
	v_mfma_f32_16x16x32_bf16 v[62:65], v[178:181], v[186:189], v[62:65]
	v_mfma_f32_16x16x32_bf16 v[62:65], v[182:185], v[190:193], v[62:65]
	v_mfma_f32_16x16x32_bf16 v[54:57], v[178:181], v[196:199], v[54:57]
	v_mfma_f32_16x16x32_bf16 v[54:57], v[182:185], v[200:203], v[54:57]
	v_mfma_f32_16x16x32_bf16 v[46:49], v[178:181], v[204:207], v[46:49]
	v_mfma_f32_16x16x32_bf16 v[46:49], v[182:185], v[208:211], v[46:49]
	v_mfma_f32_16x16x32_bf16 v[38:41], v[178:181], v[212:215], v[38:41]
	v_mfma_f32_16x16x32_bf16 v[38:41], v[182:185], v[246:249], v[38:41]
	s_setprio 0
	s_barrier
	s_add_i32 s93, s83, s2
	v_lshl_add_u64 v[216:217], s[62:63], 0, v[152:153]
	s_mov_b32 m0, s93
	ds_read_b128 v[186:189], v244 offset:16384
	ds_read_b128 v[190:193], v244 offset:17408
	ds_read_b128 v[196:199], v244 offset:18432
	ds_read_b128 v[200:203], v244 offset:19456
	ds_read_b128 v[204:207], v244 offset:20480
	ds_read_b128 v[208:211], v244 offset:21504
	ds_read_b128 v[212:215], v244 offset:22528
	ds_read_b128 v[246:249], v244 offset:23552
	global_load_lds_dwordx4 v[216:217], off
	s_add_i32 m0, s93, 0x2000
	s_add_u32 s94, s62, 0x100000
	v_lshl_add_u64 v[250:251], s[62:63], 0, v[156:157]
	s_addc_u32 s95, s63, 0
	s_add_i32 s93, s86, s2
	global_load_lds_dwordx4 v[250:251], off
	v_lshl_add_u64 v[4:5], s[94:95], 0, v[152:153]
	s_mov_b32 m0, s93
	v_lshl_add_u64 v[252:253], s[64:65], 0, v[150:151]
	global_load_lds_dwordx4 v[4:5], off
	v_lshl_add_u64 v[4:5], s[94:95], 0, v[156:157]
	s_add_i32 m0, s93, 0x2000
	v_lshl_add_u64 v[222:223], s[64:65], 0, v[154:155]
	global_load_lds_dwordx4 v[4:5], off
	s_mov_b32 m0, s24
	s_nop 0
	global_load_lds_dwordx4 v[252:253], off
	s_mov_b32 m0, s25
	s_nop 0
	global_load_lds_dwordx4 v[222:223], off
	s_waitcnt vmcnt(8)
	s_waitcnt lgkmcnt(0)
	s_barrier
; #define PG8_STAGE(bufoff, gbase, voff) do { _Pragma("unroll") for (int _i = 0; _i < 2; ++_i) \
;         __builtin_amdgcn_global_load_lds((const unsigned*)((const char*)(gbase) + (voff)[_i]), (PG8_LAS unsigned*)(lds + (bufoff) + ldsw + _i * 8192), 16, 0, 0); } while (0)
; #define PG8_LDA(dst, b, h) do { _Pragma("unroll") for (int m = 0; m < 4; ++m) _Pragma("unroll") for (int k = 0; k < 2; ++k) dst[m][k] = *(const PG8_LAS bf16x8*)(lds + PG8_SA(b, h) + aoff + m * 2048 + k * 1024); } while (0)
; #define PG8_LDB(dst, b, h) do { _Pragma("unroll") for (int n = 0; n < 2; ++n) _Pragma("unroll") for (int k = 0; k < 2; ++k) dst[n][k] = *(const PG8_LAS bf16x8*)(lds + PG8_SB(b, h) + boff + n * 2048 + k * 1024); } while (0)
; #define PG8_MMA(ai, bj, At, Bt) do { __builtin_amdgcn_s_setprio(1); _Pragma("unroll") for (int m = 0; m < 4; ++m) _Pragma("unroll") for (int n = 0; n < 2; ++n) _Pragma("unroll") for (int k = 0; k < 2; ++k) \
;         acc[ai][bj][m][n] = __builtin_amdgcn_mfma_f32_16x16x32_bf16(Bt[n][k], At[m][k], acc[ai][bj][m][n], 0, 0, 0); __builtin_amdgcn_s_setprio(0); } while (0)
; #define PG8_WAIT_V(n) asm volatile("s_waitcnt vmcnt(" #n ")" ::: "memory")
; #define PG8_WAIT_L(n) asm volatile("s_waitcnt lgkmcnt(" #n ")" ::: "memory")
; #define PG8_BAR __builtin_amdgcn_s_barrier()
; #define PG8_SCHED __builtin_amdgcn_sched_barrier(0)
; template <class Epi, class Sched, bool ALIGN_EPI = false, bool SP2 = false>
; __device__ __forceinline__ void gemm_phase(PG8_LAS unsigned char* lds, const Gemm g, const Sched& S, const Epi& E) {
;     ...
;             PG8_WAIT_V(8); PG8_WAIT_L(0); PG8_BAR; PG8_MMA(1, 0, At, B0); PG8_MMA(1, 1, At, B1); PG8_BAR; PG8_SCHED;
;             PG8_LDB(B0, 1, 0); PG8_LDB(B1, 1, 1); PG8_SCHED; PG8_LDA(At, 1, 0); PG8_STAGE(PG8_SA(0, 1), a2 + hstep, voffA);
;             PG8_WAIT_V(8); PG8_WAIT_L(0); PG8_BAR; PG8_MMA(0, 0, At, B0); PG8_MMA(0, 1, At, B1); PG8_BAR; PG8_SCHED;
	s_setprio 1
	s_waitcnt lgkmcnt(0)
	v_mfma_f32_16x16x32_bf16 v[114:117], v[98:101], v[186:189], v[114:117]
	v_mfma_f32_16x16x32_bf16 v[114:117], v[102:105], v[190:193], v[114:117]
	v_mfma_f32_16x16x32_bf16 v[90:93], v[98:101], v[196:199], v[90:93]
	v_mfma_f32_16x16x32_bf16 v[90:93], v[102:105], v[200:203], v[90:93]
	v_mfma_f32_16x16x32_bf16 v[82:85], v[98:101], v[204:207], v[82:85]
	v_mfma_f32_16x16x32_bf16 v[82:85], v[102:105], v[208:211], v[82:85]
	v_mfma_f32_16x16x32_bf16 v[74:77], v[98:101], v[212:215], v[74:77]
	v_mfma_f32_16x16x32_bf16 v[74:77], v[102:105], v[246:249], v[74:77]
	v_mfma_f32_16x16x32_bf16 v[110:113], v[106:109], v[186:189], v[110:113]
	v_mfma_f32_16x16x32_bf16 v[110:113], v[166:169], v[190:193], v[110:113]
	v_mfma_f32_16x16x32_bf16 v[86:89], v[106:109], v[196:199], v[86:89]
	v_mfma_f32_16x16x32_bf16 v[86:89], v[166:169], v[200:203], v[86:89]
	v_mfma_f32_16x16x32_bf16 v[78:81], v[106:109], v[204:207], v[78:81]
	v_mfma_f32_16x16x32_bf16 v[78:81], v[166:169], v[208:211], v[78:81]
	v_mfma_f32_16x16x32_bf16 v[70:73], v[106:109], v[212:215], v[70:73]
	v_mfma_f32_16x16x32_bf16 v[70:73], v[166:169], v[246:249], v[70:73]
	s_setprio 0
	s_setprio 1
	v_mfma_f32_16x16x32_bf16 v[34:37], v[170:173], v[186:189], v[34:37]
	v_mfma_f32_16x16x32_bf16 v[34:37], v[174:177], v[190:193], v[34:37]
	v_mfma_f32_16x16x32_bf16 v[26:29], v[170:173], v[196:199], v[26:29]
	v_mfma_f32_16x16x32_bf16 v[26:29], v[174:177], v[200:203], v[26:29]
	v_mfma_f32_16x16x32_bf16 v[18:21], v[170:173], v[204:207], v[18:21]
	v_mfma_f32_16x16x32_bf16 v[18:21], v[174:177], v[208:211], v[18:21]
	v_mfma_f32_16x16x32_bf16 v[10:13], v[170:173], v[212:215], v[10:13]
	v_mfma_f32_16x16x32_bf16 v[10:13], v[174:177], v[246:249], v[10:13]
	v_mfma_f32_16x16x32_bf16 v[30:33], v[178:181], v[186:189], v[30:33]
	v_mfma_f32_16x16x32_bf16 v[30:33], v[182:185], v[190:193], v[30:33]
	v_mfma_f32_16x16x32_bf16 v[22:25], v[178:181], v[196:199], v[22:25]
	v_mfma_f32_16x16x32_bf16 v[22:25], v[182:185], v[200:203], v[22:25]
	v_mfma_f32_16x16x32_bf16 v[14:17], v[178:181], v[204:207], v[14:17]
	v_mfma_f32_16x16x32_bf16 v[14:17], v[182:185], v[208:211], v[14:17]
	v_mfma_f32_16x16x32_bf16 v[4:7], v[178:181], v[212:215], v[6:9]
	v_mfma_f32_16x16x32_bf16 v[4:7], v[182:185], v[246:249], v[4:7]
	s_setprio 0
	s_barrier
	s_add_i32 s93, 0, 0x18000
	v_add_u32_e32 v3, s93, v219
	s_add_i32 s94, 0, 0x1c000
	ds_read_b128 v[98:101], v3
	ds_read_b128 v[102:105], v3 offset:1024
	ds_read_b128 v[106:109], v3 offset:2048
	ds_read_b128 v[166:169], v3 offset:3072
	v_add_u32_e32 v3, s94, v219
	ds_read_b128 v[170:173], v3
	ds_read_b128 v[174:177], v3 offset:1024
	ds_read_b128 v[178:181], v3 offset:2048
	ds_read_b128 v[182:185], v3 offset:3072
	s_add_u32 s64, s64, 0x100000
	s_addc_u32 s65, s65, 0
	s_mov_b32 m0, s26
	v_lshl_add_u64 v[8:9], s[64:65], 0, v[150:151]
	ds_read_b128 v[186:189], v244 offset:32768
	ds_read_b128 v[190:193], v244 offset:33792
	ds_read_b128 v[196:199], v244 offset:34816
	ds_read_b128 v[200:203], v244 offset:35840
	ds_read_b128 v[204:207], v244 offset:36864
	ds_read_b128 v[208:211], v244 offset:37888
	ds_read_b128 v[212:215], v244 offset:38912
	ds_read_b128 v[246:249], v244 offset:39936
	global_load_lds_dwordx4 v[8:9], off
	v_lshl_add_u64 v[8:9], s[64:65], 0, v[154:155]
	s_mov_b32 m0, s27
	s_nop 0
	global_load_lds_dwordx4 v[8:9], off
	s_waitcnt vmcnt(8)
	s_waitcnt lgkmcnt(0)
	s_barrier
	s_setprio 1
	s_waitcnt lgkmcnt(0)
	v_mfma_f32_16x16x32_bf16 v[146:149], v[98:101], v[186:189], v[146:149]
	v_mfma_f32_16x16x32_bf16 v[146:149], v[102:105], v[190:193], v[146:149]
	v_mfma_f32_16x16x32_bf16 v[138:141], v[98:101], v[196:199], v[138:141]
	v_mfma_f32_16x16x32_bf16 v[138:141], v[102:105], v[200:203], v[138:141]
	v_mfma_f32_16x16x32_bf16 v[130:133], v[98:101], v[204:207], v[130:133]
	v_mfma_f32_16x16x32_bf16 v[130:133], v[102:105], v[208:211], v[130:133]
	v_mfma_f32_16x16x32_bf16 v[122:125], v[98:101], v[212:215], v[122:125]
	v_mfma_f32_16x16x32_bf16 v[122:125], v[102:105], v[246:249], v[122:125]
	v_mfma_f32_16x16x32_bf16 v[142:145], v[106:109], v[186:189], v[142:145]
	v_mfma_f32_16x16x32_bf16 v[142:145], v[166:169], v[190:193], v[142:145]
	v_mfma_f32_16x16x32_bf16 v[134:137], v[106:109], v[196:199], v[134:137]
	v_mfma_f32_16x16x32_bf16 v[134:137], v[166:169], v[200:203], v[134:137]
	v_mfma_f32_16x16x32_bf16 v[126:129], v[106:109], v[204:207], v[126:129]
	v_mfma_f32_16x16x32_bf16 v[126:129], v[166:169], v[208:211], v[126:129]
	v_mfma_f32_16x16x32_bf16 v[118:121], v[106:109], v[212:215], v[118:121]
	v_mfma_f32_16x16x32_bf16 v[118:121], v[166:169], v[246:249], v[118:121]
	s_setprio 0
	s_setprio 1
	v_mfma_f32_16x16x32_bf16 v[66:69], v[170:173], v[186:189], v[66:69]
	v_mfma_f32_16x16x32_bf16 v[66:69], v[174:177], v[190:193], v[66:69]
	v_mfma_f32_16x16x32_bf16 v[58:61], v[170:173], v[196:199], v[58:61]
	v_mfma_f32_16x16x32_bf16 v[58:61], v[174:177], v[200:203], v[58:61]
	v_mfma_f32_16x16x32_bf16 v[50:53], v[170:173], v[204:207], v[50:53]
	v_mfma_f32_16x16x32_bf16 v[50:53], v[174:177], v[208:211], v[50:53]
	v_mfma_f32_16x16x32_bf16 v[42:45], v[170:173], v[212:215], v[42:45]
	v_mfma_f32_16x16x32_bf16 v[42:45], v[174:177], v[246:249], v[42:45]
	v_mfma_f32_16x16x32_bf16 v[62:65], v[178:181], v[186:189], v[62:65]
	v_mfma_f32_16x16x32_bf16 v[62:65], v[182:185], v[190:193], v[62:65]
	v_mfma_f32_16x16x32_bf16 v[54:57], v[178:181], v[196:199], v[54:57]
	v_mfma_f32_16x16x32_bf16 v[54:57], v[182:185], v[200:203], v[54:57]
	v_mfma_f32_16x16x32_bf16 v[46:49], v[178:181], v[204:207], v[46:49]
	v_mfma_f32_16x16x32_bf16 v[46:49], v[182:185], v[208:211], v[46:49]
	v_mfma_f32_16x16x32_bf16 v[38:41], v[178:181], v[212:215], v[38:41]
	v_mfma_f32_16x16x32_bf16 v[38:41], v[182:185], v[246:249], v[38:41]
	s_setprio 0
	s_barrier
; #define PG8_STAGE(bufoff, gbase, voff) do { _Pragma("unroll") for (int _i = 0; _i < 2; ++_i) \
;         __builtin_amdgcn_global_load_lds((const unsigned*)((const char*)(gbase) + (voff)[_i]), (PG8_LAS unsigned*)(lds + (bufoff) + ldsw + _i * 8192), 16, 0, 0); } while (0)
; #define PG8_LDA(dst, b, h) do { _Pragma("unroll") for (int m = 0; m < 4; ++m) _Pragma("unroll") for (int k = 0; k < 2; ++k) dst[m][k] = *(const PG8_LAS bf16x8*)(lds + PG8_SA(b, h) + aoff + m * 2048 + k * 1024); } while (0)
; #define PG8_MMA(ai, bj, At, Bt) do { __builtin_amdgcn_s_setprio(1); _Pragma("unroll") for (int m = 0; m < 4; ++m) _Pragma("unroll") for (int n = 0; n < 2; ++n) _Pragma("unroll") for (int k = 0; k < 2; ++k) \
;         acc[ai][bj][m][n] = __builtin_amdgcn_mfma_f32_16x16x32_bf16(Bt[n][k], At[m][k], acc[ai][bj][m][n], 0, 0, 0); __builtin_amdgcn_s_setprio(0); } while (0)
; #define PG8_WAIT_V(n) asm volatile("s_waitcnt vmcnt(" #n ")" ::: "memory")
; #define PG8_WAIT_L(n) asm volatile("s_waitcnt lgkmcnt(" #n ")" ::: "memory")
; #define PG8_BAR __builtin_amdgcn_s_barrier()
; #define PG8_SCHED __builtin_amdgcn_sched_barrier(0)
; template <class Epi, class Sched, bool ALIGN_EPI = false, bool SP2 = false>
; __device__ __forceinline__ void gemm_phase(PG8_LAS unsigned char* lds, const Gemm g, const Sched& S, const Epi& E) {
;     ...
;             PG8_LDA(At, 1, 1); PG8_STAGE(PG8_SB(1, 0), b3, voffB); PG8_STAGE(PG8_SB(1, 1), b3 + hstep, voffB); PG8_STAGE(PG8_SA(1, 0), a3, voffA);
;             PG8_WAIT_V(8); PG8_WAIT_L(0); PG8_BAR; PG8_MMA(1, 0, At, B0); PG8_MMA(1, 1, At, B1); PG8_BAR; PG8_SCHED;
	s_add_i32 s64, s93, s2
	v_lshl_add_u64 v[8:9], v[216:217], 0, s[14:15]
	s_mov_b32 m0, s64
	ds_read_b128 v[186:189], v244 offset:49152
	ds_read_b128 v[190:193], v244 offset:50176
	ds_read_b128 v[196:199], v244 offset:51200
	ds_read_b128 v[200:203], v244 offset:52224
	ds_read_b128 v[204:207], v244 offset:53248
	ds_read_b128 v[208:211], v244 offset:54272
	ds_read_b128 v[212:215], v244 offset:55296
	ds_read_b128 v[246:249], v244 offset:56320
	global_load_lds_dwordx4 v[8:9], off
	s_add_i32 m0, s64, 0x2000
	s_add_u32 s62, s62, 0x100080
	v_lshl_add_u64 v[8:9], v[250:251], 0, s[14:15]
	s_addc_u32 s63, s63, 0
	s_add_i32 s64, s94, s2
	global_load_lds_dwordx4 v[8:9], off
	v_lshl_add_u64 v[8:9], s[62:63], 0, v[152:153]
	s_mov_b32 m0, s64
	s_nop 0
	global_load_lds_dwordx4 v[8:9], off
	v_lshl_add_u64 v[8:9], s[62:63], 0, v[156:157]
	s_add_i32 m0, s64, 0x2000
	s_nop 0
	global_load_lds_dwordx4 v[8:9], off
	v_lshl_add_u64 v[8:9], v[252:253], 0, s[14:15]
	s_mov_b32 m0, s66
	s_nop 0
	global_load_lds_dwordx4 v[8:9], off
	v_lshl_add_u64 v[8:9], v[222:223], 0, s[14:15]
	s_mov_b32 m0, s67
	s_nop 0
	global_load_lds_dwordx4 v[8:9], off
	s_waitcnt vmcnt(8)
	s_waitcnt lgkmcnt(0)
	s_barrier
	s_setprio 1
	s_waitcnt lgkmcnt(0)
	v_mfma_f32_16x16x32_bf16 v[114:117], v[98:101], v[186:189], v[114:117]
	v_mfma_f32_16x16x32_bf16 v[114:117], v[102:105], v[190:193], v[114:117]
	v_mfma_f32_16x16x32_bf16 v[90:93], v[98:101], v[196:199], v[90:93]
	v_mfma_f32_16x16x32_bf16 v[90:93], v[102:105], v[200:203], v[90:93]
	v_mfma_f32_16x16x32_bf16 v[82:85], v[98:101], v[204:207], v[82:85]
	v_mfma_f32_16x16x32_bf16 v[82:85], v[102:105], v[208:211], v[82:85]
	v_mfma_f32_16x16x32_bf16 v[74:77], v[98:101], v[212:215], v[74:77]
	v_mfma_f32_16x16x32_bf16 v[74:77], v[102:105], v[246:249], v[74:77]
	v_mfma_f32_16x16x32_bf16 v[110:113], v[106:109], v[186:189], v[110:113]
	v_mfma_f32_16x16x32_bf16 v[110:113], v[166:169], v[190:193], v[110:113]
	v_mfma_f32_16x16x32_bf16 v[86:89], v[106:109], v[196:199], v[86:89]
	v_mfma_f32_16x16x32_bf16 v[86:89], v[166:169], v[200:203], v[86:89]
	v_mfma_f32_16x16x32_bf16 v[78:81], v[106:109], v[204:207], v[78:81]
	v_mfma_f32_16x16x32_bf16 v[78:81], v[166:169], v[208:211], v[78:81]
	v_mfma_f32_16x16x32_bf16 v[70:73], v[106:109], v[212:215], v[70:73]
	v_mfma_f32_16x16x32_bf16 v[70:73], v[166:169], v[246:249], v[70:73]
	s_setprio 0
	s_setprio 1
	v_mfma_f32_16x16x32_bf16 v[34:37], v[170:173], v[186:189], v[34:37]
	v_mfma_f32_16x16x32_bf16 v[34:37], v[174:177], v[190:193], v[34:37]
	v_mfma_f32_16x16x32_bf16 v[26:29], v[170:173], v[196:199], v[26:29]
	v_mfma_f32_16x16x32_bf16 v[26:29], v[174:177], v[200:203], v[26:29]
	v_mfma_f32_16x16x32_bf16 v[18:21], v[170:173], v[204:207], v[18:21]
	v_mfma_f32_16x16x32_bf16 v[18:21], v[174:177], v[208:211], v[18:21]
	v_mfma_f32_16x16x32_bf16 v[8:11], v[170:173], v[212:215], v[10:13]
	v_mfma_f32_16x16x32_bf16 v[10:13], v[174:177], v[246:249], v[8:11]
	v_mfma_f32_16x16x32_bf16 v[30:33], v[178:181], v[186:189], v[30:33]
	v_mfma_f32_16x16x32_bf16 v[30:33], v[182:185], v[190:193], v[30:33]
	v_mfma_f32_16x16x32_bf16 v[22:25], v[178:181], v[196:199], v[22:25]
	v_mfma_f32_16x16x32_bf16 v[22:25], v[182:185], v[200:203], v[22:25]
	v_mfma_f32_16x16x32_bf16 v[14:17], v[178:181], v[204:207], v[14:17]
	v_mfma_f32_16x16x32_bf16 v[14:17], v[182:185], v[208:211], v[14:17]
	v_mfma_f32_16x16x32_bf16 v[4:7], v[178:181], v[212:215], v[4:7]
	v_mfma_f32_16x16x32_bf16 v[6:9], v[182:185], v[246:249], v[4:7]
	s_setprio 0
	s_barrier
	s_add_i32 s92, s92, 2
	s_add_u32 s60, s60, 0x100
	s_addc_u32 s61, s61, 0
	s_cmp_gt_u32 s92, 61
	s_cbranch_scc1 .LBB0_914

; #define PG8_STAGE(bufoff, gbase, voff) do { _Pragma("unroll") for (int _i = 0; _i < 2; ++_i) \
;         __builtin_amdgcn_global_load_lds((const unsigned*)((const char*)(gbase) + (voff)[_i]), (PG8_LAS unsigned*)(lds + (bufoff) + ldsw + _i * 8192), 16, 0, 0); } while (0)
; #define PG8_LDA(dst, b, h) do { _Pragma("unroll") for (int m = 0; m < 4; ++m) _Pragma("unroll") for (int k = 0; k < 2; ++k) dst[m][k] = *(const PG8_LAS bf16x8*)(lds + PG8_SA(b, h) + aoff + m * 2048 + k * 1024); } while (0)
; #define PG8_LDB(dst, b, h) do { _Pragma("unroll") for (int n = 0; n < 2; ++n) _Pragma("unroll") for (int k = 0; k < 2; ++k) dst[n][k] = *(const PG8_LAS bf16x8*)(lds + PG8_SB(b, h) + boff + n * 2048 + k * 1024); } while (0)
; #define PG8_MMA(ai, bj, At, Bt) do { __builtin_amdgcn_s_setprio(1); _Pragma("unroll") for (int m = 0; m < 4; ++m) _Pragma("unroll") for (int n = 0; n < 2; ++n) _Pragma("unroll") for (int k = 0; k < 2; ++k) \
;         acc[ai][bj][m][n] = __builtin_amdgcn_mfma_f32_16x16x32_bf16(Bt[n][k], At[m][k], acc[ai][bj][m][n], 0, 0, 0); __builtin_amdgcn_s_setprio(0); } while (0)
; #define PG8_BAR __builtin_amdgcn_s_barrier()
; template <class Epi, class Sched, bool ALIGN_EPI = false, bool SP2 = false>
; __device__ __forceinline__ void gemm_phase(PG8_LAS unsigned char* lds, const Gemm g, const Sched& S, const Epi& E) {
;     ...
;             const bool last = (t == nt - 2);
;             const char* a1 = cA + (size_t)(t + 1) * kstep;
;             const char* a2 = last ? nA : cA + (size_t)(t + 2) * kstep; const char* b2 = last ? nB : cB + (size_t)(t + 2) * kstep;
;             const char* a3 = a2 + kstep; const char* b3 = b2 + kstep;
;             if (last && has_next) S.a_ready(nxt);
;             if constexpr (Epi::MIDK) { if (t == (nt >> 1)) { E.midk(acc, wr, fr); asm volatile("s_waitcnt lgkmcnt(0)" ::: "memory"); } }
;             if constexpr (SP2) {
;             PG8_LDB(B0, 0, 0); PG8_LDB(B1, 0, 1); PG8_SCHED; PG8_LDA(At, 0, 0); PG8_STAGE(PG8_SA(1, 1), a1 + hstep, voffA);
;             PG8_WAIT_V(8); PG8_WAIT_L(0); PG8_BAR; PG8_MMA(0, 0, At, B0); PG8_MMA(0, 1, At, B1); PG8_BAR; PG8_SCHED;
;             PG8_LDA(At, 0, 1); PG8_STAGE(PG8_SB(0, 0), b2, voffB); PG8_STAGE(PG8_SB(0, 1), b2 + hstep, voffB); PG8_STAGE(PG8_SA(0, 0), a2, voffA);
;             PG8_WAIT_V(8); PG8_WAIT_L(0); PG8_BAR; PG8_MMA(1, 0, At, B0); PG8_MMA(1, 1, At, B1); PG8_BAR; PG8_SCHED;
.LBB0_1251:
	ds_read_b128 v[130:133], v177
	ds_read_b128 v[134:137], v177 offset:1024
	ds_read_b128 v[138:141], v177 offset:2048
	ds_read_b128 v[142:145], v177 offset:3072
	ds_read_b128 v[162:165], v178
	ds_read_b128 v[180:183], v178 offset:1024
	ds_read_b128 v[184:187], v178 offset:2048
	ds_read_b128 v[188:191], v178 offset:3072
	s_add_u32 s40, s36, 0xfff00080
	s_addc_u32 s41, s37, -1
	s_cmp_eq_u32 s58, 60
	s_cselect_b32 s43, s15, s41
	s_cselect_b32 s42, s17, s40
	s_cselect_b32 s41, s54, s57
	s_cselect_b32 s40, s55, s56
	ds_read_b128 v[196:199], v179
	ds_read_b128 v[200:203], v179 offset:1024
	ds_read_b128 v[204:207], v179 offset:2048
	ds_read_b128 v[208:211], v179 offset:3072
	ds_read_b128 v[212:215], v179 offset:4096
	ds_read_b128 v[220:223], v179 offset:5120
	ds_read_b128 v[224:227], v179 offset:6144
	ds_read_b128 v[228:231], v179 offset:7168
	s_add_i32 m0, s24, 0xc000
	s_nop 0
	global_load_lds_dwordx4 v146, s[36:37]
	s_add_i32 m0, s24, 0xe000
	s_nop 0
	global_load_lds_dwordx4 v150, s[36:37]
	s_waitcnt lgkmcnt(0)
	s_setprio 1
	v_mfma_f32_16x16x32_bf16 v[126:129], v[130:133], v[196:199], v[126:129]
	v_mfma_f32_16x16x32_bf16 v[126:129], v[134:137], v[200:203], v[126:129]
	v_mfma_f32_16x16x32_bf16 v[110:113], v[130:133], v[204:207], v[110:113]
	v_mfma_f32_16x16x32_bf16 v[110:113], v[134:137], v[208:211], v[110:113]
	v_mfma_f32_16x16x32_bf16 v[94:97], v[130:133], v[212:215], v[94:97]
	v_mfma_f32_16x16x32_bf16 v[94:97], v[134:137], v[220:223], v[94:97]
	v_mfma_f32_16x16x32_bf16 v[78:81], v[130:133], v[224:227], v[78:81]
	v_mfma_f32_16x16x32_bf16 v[78:81], v[134:137], v[228:231], v[78:81]
	v_mfma_f32_16x16x32_bf16 v[122:125], v[138:141], v[196:199], v[122:125]
	v_mfma_f32_16x16x32_bf16 v[122:125], v[142:145], v[200:203], v[122:125]
	v_mfma_f32_16x16x32_bf16 v[106:109], v[138:141], v[204:207], v[106:109]
	v_mfma_f32_16x16x32_bf16 v[106:109], v[142:145], v[208:211], v[106:109]
	v_mfma_f32_16x16x32_bf16 v[90:93], v[138:141], v[212:215], v[90:93]
	v_mfma_f32_16x16x32_bf16 v[90:93], v[142:145], v[220:223], v[90:93]
	v_mfma_f32_16x16x32_bf16 v[74:77], v[138:141], v[224:227], v[74:77]
	v_mfma_f32_16x16x32_bf16 v[74:77], v[142:145], v[228:231], v[74:77]
	v_mfma_f32_16x16x32_bf16 v[118:121], v[162:165], v[196:199], v[118:121]
	v_mfma_f32_16x16x32_bf16 v[118:121], v[180:183], v[200:203], v[118:121]
	v_mfma_f32_16x16x32_bf16 v[102:105], v[162:165], v[204:207], v[102:105]
	v_mfma_f32_16x16x32_bf16 v[102:105], v[180:183], v[208:211], v[102:105]
	v_mfma_f32_16x16x32_bf16 v[86:89], v[162:165], v[212:215], v[86:89]
	v_mfma_f32_16x16x32_bf16 v[86:89], v[180:183], v[220:223], v[86:89]
	v_mfma_f32_16x16x32_bf16 v[70:73], v[162:165], v[224:227], v[70:73]
	v_mfma_f32_16x16x32_bf16 v[70:73], v[180:183], v[228:231], v[70:73]
	v_mfma_f32_16x16x32_bf16 v[114:117], v[184:187], v[196:199], v[114:117]
	v_mfma_f32_16x16x32_bf16 v[114:117], v[188:191], v[200:203], v[114:117]
	v_mfma_f32_16x16x32_bf16 v[98:101], v[184:187], v[204:207], v[98:101]
	v_mfma_f32_16x16x32_bf16 v[98:101], v[188:191], v[208:211], v[98:101]
	v_mfma_f32_16x16x32_bf16 v[82:85], v[184:187], v[212:215], v[82:85]
	v_mfma_f32_16x16x32_bf16 v[82:85], v[188:191], v[220:223], v[82:85]
	v_mfma_f32_16x16x32_bf16 v[66:69], v[184:187], v[224:227], v[66:69]
	v_mfma_f32_16x16x32_bf16 v[66:69], v[188:191], v[228:231], v[66:69]
	s_setprio 0
	s_waitcnt vmcnt(8)
	s_barrier
	ds_read_b128 v[196:199], v179 offset:16384
	ds_read_b128 v[200:203], v179 offset:17408
	ds_read_b128 v[204:207], v179 offset:18432
	ds_read_b128 v[208:211], v179 offset:19456
	ds_read_b128 v[212:215], v179 offset:20480
	ds_read_b128 v[220:223], v179 offset:21504
	ds_read_b128 v[224:227], v179 offset:22528
	ds_read_b128 v[228:231], v179 offset:23552
	s_add_u32 vcc_lo, s40, 0x100000
	s_addc_u32 vcc_hi, s41, 0
	s_add_i32 m0, s24, 0x10000
	s_nop 0
	global_load_lds_dwordx4 v148, s[40:41]
	s_add_i32 m0, s24, 0x12000
	s_nop 0
	global_load_lds_dwordx4 v152, s[40:41]
	s_add_i32 m0, s24, 0x14000
	s_nop 0
	global_load_lds_dwordx4 v148, vcc
	s_add_i32 m0, s24, 0x16000
	s_nop 0
	global_load_lds_dwordx4 v152, vcc
	s_mov_b32 m0, s24
	s_nop 0
	global_load_lds_dwordx4 v146, s[42:43]
	s_add_i32 m0, s24, 0x2000
	s_nop 0
	global_load_lds_dwordx4 v150, s[42:43]
	s_waitcnt lgkmcnt(0)
	s_setprio 1
	v_mfma_f32_16x16x32_bf16 v[62:65], v[130:133], v[196:199], v[62:65]
	v_mfma_f32_16x16x32_bf16 v[62:65], v[134:137], v[200:203], v[62:65]
	v_mfma_f32_16x16x32_bf16 v[46:49], v[130:133], v[204:207], v[46:49]
	v_mfma_f32_16x16x32_bf16 v[46:49], v[134:137], v[208:211], v[46:49]
	v_mfma_f32_16x16x32_bf16 v[30:33], v[130:133], v[212:215], v[30:33]
	v_mfma_f32_16x16x32_bf16 v[30:33], v[134:137], v[220:223], v[30:33]
	v_mfma_f32_16x16x32_bf16 v[14:17], v[130:133], v[224:227], v[14:17]
	v_mfma_f32_16x16x32_bf16 v[14:17], v[134:137], v[228:231], v[14:17]
	v_mfma_f32_16x16x32_bf16 v[58:61], v[138:141], v[196:199], v[58:61]
	v_mfma_f32_16x16x32_bf16 v[58:61], v[142:145], v[200:203], v[58:61]
	v_mfma_f32_16x16x32_bf16 v[42:45], v[138:141], v[204:207], v[42:45]
	v_mfma_f32_16x16x32_bf16 v[42:45], v[142:145], v[208:211], v[42:45]
	v_mfma_f32_16x16x32_bf16 v[26:29], v[138:141], v[212:215], v[26:29]
	v_mfma_f32_16x16x32_bf16 v[26:29], v[142:145], v[220:223], v[26:29]
	v_mfma_f32_16x16x32_bf16 v[10:13], v[138:141], v[224:227], v[10:13]
	v_mfma_f32_16x16x32_bf16 v[10:13], v[142:145], v[228:231], v[10:13]
	v_mfma_f32_16x16x32_bf16 v[54:57], v[162:165], v[196:199], v[54:57]
	v_mfma_f32_16x16x32_bf16 v[54:57], v[180:183], v[200:203], v[54:57]
	v_mfma_f32_16x16x32_bf16 v[38:41], v[162:165], v[204:207], v[38:41]
	v_mfma_f32_16x16x32_bf16 v[38:41], v[180:183], v[208:211], v[38:41]
	v_mfma_f32_16x16x32_bf16 v[22:25], v[162:165], v[212:215], v[22:25]
	v_mfma_f32_16x16x32_bf16 v[22:25], v[180:183], v[220:223], v[22:25]
	v_mfma_f32_16x16x32_bf16 v[6:9], v[162:165], v[224:227], v[6:9]
	v_mfma_f32_16x16x32_bf16 v[6:9], v[180:183], v[228:231], v[6:9]
	v_mfma_f32_16x16x32_bf16 v[50:53], v[184:187], v[196:199], v[50:53]
	v_mfma_f32_16x16x32_bf16 v[50:53], v[188:191], v[200:203], v[50:53]
	v_mfma_f32_16x16x32_bf16 v[34:37], v[184:187], v[204:207], v[34:37]
	v_mfma_f32_16x16x32_bf16 v[34:37], v[188:191], v[208:211], v[34:37]
	v_mfma_f32_16x16x32_bf16 v[18:21], v[184:187], v[212:215], v[18:21]
	v_mfma_f32_16x16x32_bf16 v[18:21], v[188:191], v[220:223], v[18:21]
	v_mfma_f32_16x16x32_bf16 v[2:5], v[184:187], v[224:227], v[2:5]
	v_mfma_f32_16x16x32_bf16 v[2:5], v[188:191], v[228:231], v[2:5]
	s_setprio 0
	s_waitcnt vmcnt(8)
	s_barrier
; #define PG8_STAGE(bufoff, gbase, voff) do { _Pragma("unroll") for (int _i = 0; _i < 2; ++_i) \
;         __builtin_amdgcn_global_load_lds((const unsigned*)((const char*)(gbase) + (voff)[_i]), (PG8_LAS unsigned*)(lds + (bufoff) + ldsw + _i * 8192), 16, 0, 0); } while (0)
; #define PG8_LDA(dst, b, h) do { _Pragma("unroll") for (int m = 0; m < 4; ++m) _Pragma("unroll") for (int k = 0; k < 2; ++k) dst[m][k] = *(const PG8_LAS bf16x8*)(lds + PG8_SA(b, h) + aoff + m * 2048 + k * 1024); } while (0)
; #define PG8_LDB(dst, b, h) do { _Pragma("unroll") for (int n = 0; n < 2; ++n) _Pragma("unroll") for (int k = 0; k < 2; ++k) dst[n][k] = *(const PG8_LAS bf16x8*)(lds + PG8_SB(b, h) + boff + n * 2048 + k * 1024); } while (0)
; #define PG8_MMA(ai, bj, At, Bt) do { __builtin_amdgcn_s_setprio(1); _Pragma("unroll") for (int m = 0; m < 4; ++m) _Pragma("unroll") for (int n = 0; n < 2; ++n) _Pragma("unroll") for (int k = 0; k < 2; ++k) \
;         acc[ai][bj][m][n] = __builtin_amdgcn_mfma_f32_16x16x32_bf16(Bt[n][k], At[m][k], acc[ai][bj][m][n], 0, 0, 0); __builtin_amdgcn_s_setprio(0); } while (0)
; #define PG8_WAIT_V(n) asm volatile("s_waitcnt vmcnt(" #n ")" ::: "memory")
; #define PG8_WAIT_L(n) asm volatile("s_waitcnt lgkmcnt(" #n ")" ::: "memory")
; #define PG8_BAR __builtin_amdgcn_s_barrier()
; #define PG8_SCHED __builtin_amdgcn_sched_barrier(0)
; template <class Epi, class Sched, bool ALIGN_EPI = false, bool SP2 = false>
; __device__ __forceinline__ void gemm_phase(PG8_LAS unsigned char* lds, const Gemm g, const Sched& S, const Epi& E) {
;     ...
;             PG8_LDB(B0, 1, 0); PG8_LDB(B1, 1, 1); PG8_SCHED; PG8_LDA(At, 1, 0); PG8_STAGE(PG8_SA(0, 1), a2 + hstep, voffA);
;             PG8_WAIT_V(8); PG8_WAIT_L(0); PG8_BAR; PG8_MMA(0, 0, At, B0); PG8_MMA(0, 1, At, B1); PG8_BAR; PG8_SCHED;
;             PG8_LDA(At, 1, 1); PG8_STAGE(PG8_SB(1, 0), b3, voffB); PG8_STAGE(PG8_SB(1, 1), b3 + hstep, voffB); PG8_STAGE(PG8_SA(1, 0), a3, voffA);
;             PG8_WAIT_V(8); PG8_WAIT_L(0); PG8_BAR; PG8_MMA(1, 0, At, B0); PG8_MMA(1, 1, At, B1); PG8_BAR; PG8_SCHED;
	s_add_i32 s59, 0, 0x18000
	s_add_i32 s60, 0, 0x1c000
	v_add_u32_e32 v142, s59, v166
	v_add_u32_e32 v188, s60, v166
	ds_read_b128 v[130:133], v142
	ds_read_b128 v[134:137], v142 offset:1024
	ds_read_b128 v[138:141], v142 offset:2048
	ds_read_b128 v[142:145], v142 offset:3072
	ds_read_b128 v[162:165], v188
	ds_read_b128 v[180:183], v188 offset:1024
	ds_read_b128 v[184:187], v188 offset:2048
	ds_read_b128 v[188:191], v188 offset:3072
	ds_read_b128 v[196:199], v179 offset:32768
	ds_read_b128 v[200:203], v179 offset:33792
	ds_read_b128 v[204:207], v179 offset:34816
	ds_read_b128 v[208:211], v179 offset:35840
	ds_read_b128 v[212:215], v179 offset:36864
	ds_read_b128 v[220:223], v179 offset:37888
	ds_read_b128 v[224:227], v179 offset:38912
	ds_read_b128 v[228:231], v179 offset:39936
	s_add_u32 vcc_lo, s42, 0x100000
	s_addc_u32 vcc_hi, s43, 0
	s_add_i32 m0, s24, 0x4000
	s_nop 0
	global_load_lds_dwordx4 v146, vcc
	s_add_i32 m0, s24, 0x6000
	s_nop 0
	global_load_lds_dwordx4 v150, vcc
	s_waitcnt lgkmcnt(0)
	s_setprio 1
	v_mfma_f32_16x16x32_bf16 v[126:129], v[130:133], v[196:199], v[126:129]
	v_mfma_f32_16x16x32_bf16 v[126:129], v[134:137], v[200:203], v[126:129]
	v_mfma_f32_16x16x32_bf16 v[110:113], v[130:133], v[204:207], v[110:113]
	v_mfma_f32_16x16x32_bf16 v[110:113], v[134:137], v[208:211], v[110:113]
	v_mfma_f32_16x16x32_bf16 v[94:97], v[130:133], v[212:215], v[94:97]
	v_mfma_f32_16x16x32_bf16 v[94:97], v[134:137], v[220:223], v[94:97]
	v_mfma_f32_16x16x32_bf16 v[78:81], v[130:133], v[224:227], v[78:81]
	v_mfma_f32_16x16x32_bf16 v[78:81], v[134:137], v[228:231], v[78:81]
	v_mfma_f32_16x16x32_bf16 v[122:125], v[138:141], v[196:199], v[122:125]
	v_mfma_f32_16x16x32_bf16 v[122:125], v[142:145], v[200:203], v[122:125]
	v_mfma_f32_16x16x32_bf16 v[106:109], v[138:141], v[204:207], v[106:109]
	v_mfma_f32_16x16x32_bf16 v[106:109], v[142:145], v[208:211], v[106:109]
	v_mfma_f32_16x16x32_bf16 v[90:93], v[138:141], v[212:215], v[90:93]
	v_mfma_f32_16x16x32_bf16 v[90:93], v[142:145], v[220:223], v[90:93]
	v_mfma_f32_16x16x32_bf16 v[74:77], v[138:141], v[224:227], v[74:77]
	v_mfma_f32_16x16x32_bf16 v[74:77], v[142:145], v[228:231], v[74:77]
	v_mfma_f32_16x16x32_bf16 v[118:121], v[162:165], v[196:199], v[118:121]
	v_mfma_f32_16x16x32_bf16 v[118:121], v[180:183], v[200:203], v[118:121]
	v_mfma_f32_16x16x32_bf16 v[102:105], v[162:165], v[204:207], v[102:105]
	v_mfma_f32_16x16x32_bf16 v[102:105], v[180:183], v[208:211], v[102:105]
	v_mfma_f32_16x16x32_bf16 v[86:89], v[162:165], v[212:215], v[86:89]
	v_mfma_f32_16x16x32_bf16 v[86:89], v[180:183], v[220:223], v[86:89]
	v_mfma_f32_16x16x32_bf16 v[70:73], v[162:165], v[224:227], v[70:73]
	v_mfma_f32_16x16x32_bf16 v[70:73], v[180:183], v[228:231], v[70:73]
	v_mfma_f32_16x16x32_bf16 v[114:117], v[184:187], v[196:199], v[114:117]
	v_mfma_f32_16x16x32_bf16 v[114:117], v[188:191], v[200:203], v[114:117]
	v_mfma_f32_16x16x32_bf16 v[98:101], v[184:187], v[204:207], v[98:101]
	v_mfma_f32_16x16x32_bf16 v[98:101], v[188:191], v[208:211], v[98:101]
	v_mfma_f32_16x16x32_bf16 v[82:85], v[184:187], v[212:215], v[82:85]
	v_mfma_f32_16x16x32_bf16 v[82:85], v[188:191], v[220:223], v[82:85]
	v_mfma_f32_16x16x32_bf16 v[66:69], v[184:187], v[224:227], v[66:69]
	v_mfma_f32_16x16x32_bf16 v[66:69], v[188:191], v[228:231], v[66:69]
	s_setprio 0
	s_waitcnt vmcnt(8)
	s_barrier
	ds_read_b128 v[196:199], v179 offset:49152
	ds_read_b128 v[200:203], v179 offset:50176
	ds_read_b128 v[204:207], v179 offset:51200
	ds_read_b128 v[208:211], v179 offset:52224
	ds_read_b128 v[212:215], v179 offset:53248
	ds_read_b128 v[220:223], v179 offset:54272
	ds_read_b128 v[224:227], v179 offset:55296
	ds_read_b128 v[228:231], v179 offset:56320
	s_add_u32 s60, s40, 0x80
	s_addc_u32 s61, s41, 0
	s_add_u32 vcc_lo, s60, 0x100000
	s_addc_u32 vcc_hi, s61, 0
	s_add_i32 m0, s24, 0x18000
	s_nop 0
	global_load_lds_dwordx4 v148, s[60:61]
	s_add_i32 m0, s24, 0x1a000
	s_nop 0
	global_load_lds_dwordx4 v152, s[60:61]
	s_add_i32 m0, s24, 0x1c000
	s_nop 0
	global_load_lds_dwordx4 v148, vcc
	s_add_i32 m0, s24, 0x1e000
	s_nop 0
	global_load_lds_dwordx4 v152, vcc
	s_add_u32 s60, s42, 0x80
	s_addc_u32 s61, s43, 0
	s_add_i32 m0, s24, 0x8000
	s_nop 0
	global_load_lds_dwordx4 v146, s[60:61]
	s_add_i32 m0, s24, 0xa000
	s_nop 0
	global_load_lds_dwordx4 v150, s[60:61]
	s_waitcnt lgkmcnt(0)
	s_setprio 1
	v_mfma_f32_16x16x32_bf16 v[62:65], v[130:133], v[196:199], v[62:65]
	v_mfma_f32_16x16x32_bf16 v[62:65], v[134:137], v[200:203], v[62:65]
	v_mfma_f32_16x16x32_bf16 v[46:49], v[130:133], v[204:207], v[46:49]
	v_mfma_f32_16x16x32_bf16 v[46:49], v[134:137], v[208:211], v[46:49]
	v_mfma_f32_16x16x32_bf16 v[30:33], v[130:133], v[212:215], v[30:33]
	v_mfma_f32_16x16x32_bf16 v[30:33], v[134:137], v[220:223], v[30:33]
	v_mfma_f32_16x16x32_bf16 v[14:17], v[130:133], v[224:227], v[14:17]
	v_mfma_f32_16x16x32_bf16 v[14:17], v[134:137], v[228:231], v[14:17]
	v_mfma_f32_16x16x32_bf16 v[58:61], v[138:141], v[196:199], v[58:61]
	v_mfma_f32_16x16x32_bf16 v[58:61], v[142:145], v[200:203], v[58:61]
	v_mfma_f32_16x16x32_bf16 v[42:45], v[138:141], v[204:207], v[42:45]
	v_mfma_f32_16x16x32_bf16 v[42:45], v[142:145], v[208:211], v[42:45]
	v_mfma_f32_16x16x32_bf16 v[26:29], v[138:141], v[212:215], v[26:29]
	v_mfma_f32_16x16x32_bf16 v[26:29], v[142:145], v[220:223], v[26:29]
	v_mfma_f32_16x16x32_bf16 v[10:13], v[138:141], v[224:227], v[10:13]
	v_mfma_f32_16x16x32_bf16 v[10:13], v[142:145], v[228:231], v[10:13]
	v_mfma_f32_16x16x32_bf16 v[54:57], v[162:165], v[196:199], v[54:57]
	v_mfma_f32_16x16x32_bf16 v[54:57], v[180:183], v[200:203], v[54:57]
	v_mfma_f32_16x16x32_bf16 v[38:41], v[162:165], v[204:207], v[38:41]
	v_mfma_f32_16x16x32_bf16 v[38:41], v[180:183], v[208:211], v[38:41]
	v_mfma_f32_16x16x32_bf16 v[22:25], v[162:165], v[212:215], v[22:25]
	v_mfma_f32_16x16x32_bf16 v[22:25], v[180:183], v[220:223], v[22:25]
	v_mfma_f32_16x16x32_bf16 v[6:9], v[162:165], v[224:227], v[6:9]
	v_mfma_f32_16x16x32_bf16 v[6:9], v[180:183], v[228:231], v[6:9]
	v_mfma_f32_16x16x32_bf16 v[50:53], v[184:187], v[196:199], v[50:53]
	v_mfma_f32_16x16x32_bf16 v[50:53], v[188:191], v[200:203], v[50:53]
	v_mfma_f32_16x16x32_bf16 v[34:37], v[184:187], v[204:207], v[34:37]
	v_mfma_f32_16x16x32_bf16 v[34:37], v[188:191], v[208:211], v[34:37]
	v_mfma_f32_16x16x32_bf16 v[18:21], v[184:187], v[212:215], v[18:21]
	v_mfma_f32_16x16x32_bf16 v[18:21], v[188:191], v[220:223], v[18:21]
	v_mfma_f32_16x16x32_bf16 v[2:5], v[184:187], v[224:227], v[2:5]
	v_mfma_f32_16x16x32_bf16 v[2:5], v[188:191], v[228:231], v[2:5]
	s_setprio 0
	s_waitcnt vmcnt(8)
	s_barrier
	s_add_i32 s58, s58, 2
	s_add_u32 s36, s36, 0x100
	s_addc_u32 s37, s37, 0
	s_add_u32 s56, s56, 0x100
	s_addc_u32 s57, s57, 0
	s_cmp_gt_u32 s58, 61
	s_cbranch_scc0 .LBB0_1251
	s_branch .Lf1_exit
; #define PG8_STAGE(bufoff, gbase, voff) do { _Pragma("unroll") for (int _i = 0; _i < 2; ++_i) \
;         __builtin_amdgcn_global_load_lds((const unsigned*)((const char*)(gbase) + (voff)[_i]), (PG8_LAS unsigned*)(lds + (bufoff) + ldsw + _i * 8192), 16, 0, 0); } while (0)
; #define PG8_LDA(dst, b, h) do { _Pragma("unroll") for (int m = 0; m < 4; ++m) _Pragma("unroll") for (int k = 0; k < 2; ++k) dst[m][k] = *(const PG8_LAS bf16x8*)(lds + PG8_SA(b, h) + aoff + m * 2048 + k * 1024); } while (0)
; #define PG8_LDB(dst, b, h) do { _Pragma("unroll") for (int n = 0; n < 2; ++n) _Pragma("unroll") for (int k = 0; k < 2; ++k) dst[n][k] = *(const PG8_LAS bf16x8*)(lds + PG8_SB(b, h) + boff + n * 2048 + k * 1024); } while (0)
; #define PG8_MMA(ai, bj, At, Bt) do { __builtin_amdgcn_s_setprio(1); _Pragma("unroll") for (int m = 0; m < 4; ++m) _Pragma("unroll") for (int n = 0; n < 2; ++n) _Pragma("unroll") for (int k = 0; k < 2; ++k) \
;         acc[ai][bj][m][n] = __builtin_amdgcn_mfma_f32_16x16x32_bf16(Bt[n][k], At[m][k], acc[ai][bj][m][n], 0, 0, 0); __builtin_amdgcn_s_setprio(0); } while (0)
; #define PG8_WAIT_V(n) asm volatile("s_waitcnt vmcnt(" #n ")" ::: "memory")
; #define PG8_WAIT_L(n) asm volatile("s_waitcnt lgkmcnt(" #n ")" ::: "memory")
; template <class Epi, class Sched, bool ALIGN_EPI = false, bool SP2 = false>
; __device__ __forceinline__ void gemm_phase(PG8_LAS unsigned char* lds, const Gemm g, const Sched& S, const Epi& E) {
;     ...
;             const bool last = (t == nt - 2);
;             const char* a1 = cA + (size_t)(t + 1) * kstep;
;             const char* a2 = last ? nA : cA + (size_t)(t + 2) * kstep; const char* b2 = last ? nB : cB + (size_t)(t + 2) * kstep;
;             const char* a3 = a2 + kstep; const char* b3 = b2 + kstep;
;             if (last && has_next) S.a_ready(nxt);
;             if constexpr (Epi::MIDK) { if (t == (nt >> 1)) { E.midk(acc, wr, fr); asm volatile("s_waitcnt lgkmcnt(0)" ::: "memory"); } }
;             if constexpr (SP2) {
;             PG8_LDB(B0, 0, 0); PG8_LDB(B1, 0, 1); PG8_SCHED; PG8_LDA(At, 0, 0); PG8_STAGE(PG8_SA(1, 1), a1 + hstep, voffA);
;             PG8_WAIT_V(8); PG8_WAIT_L(0); PG8_BAR; PG8_MMA(0, 0, At, B0); PG8_MMA(0, 1, At, B1); PG8_BAR; PG8_SCHED;
;             PG8_LDA(At, 0, 1); PG8_STAGE(PG8_SB(0, 0), b2, voffB); PG8_STAGE(PG8_SB(0, 1), b2 + hstep, voffB); PG8_STAGE(PG8_SA(0, 0), a2, voffA);
.Lf1_h1:
	ds_read_b128 v[130:133], v177
	ds_read_b128 v[134:137], v177 offset:1024
	ds_read_b128 v[138:141], v177 offset:2048
	ds_read_b128 v[142:145], v177 offset:3072
	ds_read_b128 v[162:165], v178
	ds_read_b128 v[180:183], v178 offset:1024
	ds_read_b128 v[184:187], v178 offset:2048
	ds_read_b128 v[188:191], v178 offset:3072
	s_add_u32 s40, s36, 0xfff00080
	s_addc_u32 s41, s37, -1
	s_cmp_eq_u32 s58, 60
	s_cselect_b32 s43, s15, s41
	s_cselect_b32 s42, s17, s40
	s_cselect_b32 s41, s54, s57
	s_cselect_b32 s40, s55, s56
	ds_read_b128 v[196:199], v179
	ds_read_b128 v[200:203], v179 offset:1024
	ds_read_b128 v[204:207], v179 offset:2048
	ds_read_b128 v[208:211], v179 offset:3072
	ds_read_b128 v[212:215], v179 offset:4096
	ds_read_b128 v[220:223], v179 offset:5120
	ds_read_b128 v[224:227], v179 offset:6144
	ds_read_b128 v[228:231], v179 offset:7168
	s_add_i32 m0, s24, 0xc000
	s_nop 0
	global_load_lds_dwordx4 v146, s[36:37]
	s_add_i32 m0, s24, 0xe000
	s_nop 0
	global_load_lds_dwordx4 v150, s[36:37]
	s_sleep 2
	s_waitcnt lgkmcnt(0)
	s_waitcnt vmcnt(8)
	s_barrier
	s_setprio 2
	v_mfma_f32_16x16x32_bf16 v[126:129], v[130:133], v[196:199], v[126:129]
	v_mfma_f32_16x16x32_bf16 v[126:129], v[134:137], v[200:203], v[126:129]
	v_mfma_f32_16x16x32_bf16 v[110:113], v[130:133], v[204:207], v[110:113]
	v_mfma_f32_16x16x32_bf16 v[110:113], v[134:137], v[208:211], v[110:113]
	v_mfma_f32_16x16x32_bf16 v[94:97], v[130:133], v[212:215], v[94:97]
	v_mfma_f32_16x16x32_bf16 v[94:97], v[134:137], v[220:223], v[94:97]
	v_mfma_f32_16x16x32_bf16 v[78:81], v[130:133], v[224:227], v[78:81]
	v_mfma_f32_16x16x32_bf16 v[78:81], v[134:137], v[228:231], v[78:81]
	v_mfma_f32_16x16x32_bf16 v[122:125], v[138:141], v[196:199], v[122:125]
	v_mfma_f32_16x16x32_bf16 v[122:125], v[142:145], v[200:203], v[122:125]
	v_mfma_f32_16x16x32_bf16 v[106:109], v[138:141], v[204:207], v[106:109]
	v_mfma_f32_16x16x32_bf16 v[106:109], v[142:145], v[208:211], v[106:109]
	v_mfma_f32_16x16x32_bf16 v[90:93], v[138:141], v[212:215], v[90:93]
	v_mfma_f32_16x16x32_bf16 v[90:93], v[142:145], v[220:223], v[90:93]
	v_mfma_f32_16x16x32_bf16 v[74:77], v[138:141], v[224:227], v[74:77]
	v_mfma_f32_16x16x32_bf16 v[74:77], v[142:145], v[228:231], v[74:77]
	v_mfma_f32_16x16x32_bf16 v[118:121], v[162:165], v[196:199], v[118:121]
	v_mfma_f32_16x16x32_bf16 v[118:121], v[180:183], v[200:203], v[118:121]
	v_mfma_f32_16x16x32_bf16 v[102:105], v[162:165], v[204:207], v[102:105]
	v_mfma_f32_16x16x32_bf16 v[102:105], v[180:183], v[208:211], v[102:105]
	v_mfma_f32_16x16x32_bf16 v[86:89], v[162:165], v[212:215], v[86:89]
	v_mfma_f32_16x16x32_bf16 v[86:89], v[180:183], v[220:223], v[86:89]
	v_mfma_f32_16x16x32_bf16 v[70:73], v[162:165], v[224:227], v[70:73]
	v_mfma_f32_16x16x32_bf16 v[70:73], v[180:183], v[228:231], v[70:73]
	v_mfma_f32_16x16x32_bf16 v[114:117], v[184:187], v[196:199], v[114:117]
	v_mfma_f32_16x16x32_bf16 v[114:117], v[188:191], v[200:203], v[114:117]
	v_mfma_f32_16x16x32_bf16 v[98:101], v[184:187], v[204:207], v[98:101]
	v_mfma_f32_16x16x32_bf16 v[98:101], v[188:191], v[208:211], v[98:101]
	v_mfma_f32_16x16x32_bf16 v[82:85], v[184:187], v[212:215], v[82:85]
	v_mfma_f32_16x16x32_bf16 v[82:85], v[188:191], v[220:223], v[82:85]
	v_mfma_f32_16x16x32_bf16 v[66:69], v[184:187], v[224:227], v[66:69]
	v_mfma_f32_16x16x32_bf16 v[66:69], v[188:191], v[228:231], v[66:69]
	s_setprio 0
	ds_read_b128 v[196:199], v179 offset:16384
	ds_read_b128 v[200:203], v179 offset:17408
	ds_read_b128 v[204:207], v179 offset:18432
	ds_read_b128 v[208:211], v179 offset:19456
	ds_read_b128 v[212:215], v179 offset:20480
	ds_read_b128 v[220:223], v179 offset:21504
	ds_read_b128 v[224:227], v179 offset:22528
	ds_read_b128 v[228:231], v179 offset:23552
	s_add_u32 vcc_lo, s40, 0x100000
	s_addc_u32 vcc_hi, s41, 0
	s_add_i32 m0, s24, 0x10000
	s_nop 0
	global_load_lds_dwordx4 v148, s[40:41]
	s_add_i32 m0, s24, 0x12000
	s_nop 0
	global_load_lds_dwordx4 v152, s[40:41]
	s_add_i32 m0, s24, 0x14000
	s_nop 0
	global_load_lds_dwordx4 v148, vcc
	s_add_i32 m0, s24, 0x16000
	s_nop 0
	global_load_lds_dwordx4 v152, vcc
	s_mov_b32 m0, s24
	s_nop 0
	global_load_lds_dwordx4 v146, s[42:43]
	s_add_i32 m0, s24, 0x2000
	s_nop 0
	global_load_lds_dwordx4 v150, s[42:43]
	s_sleep 2
	s_waitcnt lgkmcnt(0)
	s_waitcnt vmcnt(8)
	s_barrier
; #define PG8_STAGE(bufoff, gbase, voff) do { _Pragma("unroll") for (int _i = 0; _i < 2; ++_i) \
;         __builtin_amdgcn_global_load_lds((const unsigned*)((const char*)(gbase) + (voff)[_i]), (PG8_LAS unsigned*)(lds + (bufoff) + ldsw + _i * 8192), 16, 0, 0); } while (0)
; #define PG8_LDA(dst, b, h) do { _Pragma("unroll") for (int m = 0; m < 4; ++m) _Pragma("unroll") for (int k = 0; k < 2; ++k) dst[m][k] = *(const PG8_LAS bf16x8*)(lds + PG8_SA(b, h) + aoff + m * 2048 + k * 1024); } while (0)
; #define PG8_LDB(dst, b, h) do { _Pragma("unroll") for (int n = 0; n < 2; ++n) _Pragma("unroll") for (int k = 0; k < 2; ++k) dst[n][k] = *(const PG8_LAS bf16x8*)(lds + PG8_SB(b, h) + boff + n * 2048 + k * 1024); } while (0)
; #define PG8_MMA(ai, bj, At, Bt) do { __builtin_amdgcn_s_setprio(1); _Pragma("unroll") for (int m = 0; m < 4; ++m) _Pragma("unroll") for (int n = 0; n < 2; ++n) _Pragma("unroll") for (int k = 0; k < 2; ++k) \
;         acc[ai][bj][m][n] = __builtin_amdgcn_mfma_f32_16x16x32_bf16(Bt[n][k], At[m][k], acc[ai][bj][m][n], 0, 0, 0); __builtin_amdgcn_s_setprio(0); } while (0)
; #define PG8_WAIT_V(n) asm volatile("s_waitcnt vmcnt(" #n ")" ::: "memory")
; #define PG8_WAIT_L(n) asm volatile("s_waitcnt lgkmcnt(" #n ")" ::: "memory")
; #define PG8_BAR __builtin_amdgcn_s_barrier()
; #define PG8_SCHED __builtin_amdgcn_sched_barrier(0)
; template <class Epi, class Sched, bool ALIGN_EPI = false, bool SP2 = false>
; __device__ __forceinline__ void gemm_phase(PG8_LAS unsigned char* lds, const Gemm g, const Sched& S, const Epi& E) {
;     ...
;             PG8_WAIT_V(8); PG8_WAIT_L(0); PG8_BAR; PG8_MMA(1, 0, At, B0); PG8_MMA(1, 1, At, B1); PG8_BAR; PG8_SCHED;
;             PG8_LDB(B0, 1, 0); PG8_LDB(B1, 1, 1); PG8_SCHED; PG8_LDA(At, 1, 0); PG8_STAGE(PG8_SA(0, 1), a2 + hstep, voffA);
;             PG8_WAIT_V(8); PG8_WAIT_L(0); PG8_BAR; PG8_MMA(0, 0, At, B0); PG8_MMA(0, 1, At, B1); PG8_BAR; PG8_SCHED;
	s_setprio 2
	v_mfma_f32_16x16x32_bf16 v[62:65], v[130:133], v[196:199], v[62:65]
	v_mfma_f32_16x16x32_bf16 v[62:65], v[134:137], v[200:203], v[62:65]
	v_mfma_f32_16x16x32_bf16 v[46:49], v[130:133], v[204:207], v[46:49]
	v_mfma_f32_16x16x32_bf16 v[46:49], v[134:137], v[208:211], v[46:49]
	v_mfma_f32_16x16x32_bf16 v[30:33], v[130:133], v[212:215], v[30:33]
	v_mfma_f32_16x16x32_bf16 v[30:33], v[134:137], v[220:223], v[30:33]
	v_mfma_f32_16x16x32_bf16 v[14:17], v[130:133], v[224:227], v[14:17]
	v_mfma_f32_16x16x32_bf16 v[14:17], v[134:137], v[228:231], v[14:17]
	v_mfma_f32_16x16x32_bf16 v[58:61], v[138:141], v[196:199], v[58:61]
	v_mfma_f32_16x16x32_bf16 v[58:61], v[142:145], v[200:203], v[58:61]
	v_mfma_f32_16x16x32_bf16 v[42:45], v[138:141], v[204:207], v[42:45]
	v_mfma_f32_16x16x32_bf16 v[42:45], v[142:145], v[208:211], v[42:45]
	v_mfma_f32_16x16x32_bf16 v[26:29], v[138:141], v[212:215], v[26:29]
	v_mfma_f32_16x16x32_bf16 v[26:29], v[142:145], v[220:223], v[26:29]
	v_mfma_f32_16x16x32_bf16 v[10:13], v[138:141], v[224:227], v[10:13]
	v_mfma_f32_16x16x32_bf16 v[10:13], v[142:145], v[228:231], v[10:13]
	v_mfma_f32_16x16x32_bf16 v[54:57], v[162:165], v[196:199], v[54:57]
	v_mfma_f32_16x16x32_bf16 v[54:57], v[180:183], v[200:203], v[54:57]
	v_mfma_f32_16x16x32_bf16 v[38:41], v[162:165], v[204:207], v[38:41]
	v_mfma_f32_16x16x32_bf16 v[38:41], v[180:183], v[208:211], v[38:41]
	v_mfma_f32_16x16x32_bf16 v[22:25], v[162:165], v[212:215], v[22:25]
	v_mfma_f32_16x16x32_bf16 v[22:25], v[180:183], v[220:223], v[22:25]
	v_mfma_f32_16x16x32_bf16 v[6:9], v[162:165], v[224:227], v[6:9]
	v_mfma_f32_16x16x32_bf16 v[6:9], v[180:183], v[228:231], v[6:9]
	v_mfma_f32_16x16x32_bf16 v[50:53], v[184:187], v[196:199], v[50:53]
	v_mfma_f32_16x16x32_bf16 v[50:53], v[188:191], v[200:203], v[50:53]
	v_mfma_f32_16x16x32_bf16 v[34:37], v[184:187], v[204:207], v[34:37]
	v_mfma_f32_16x16x32_bf16 v[34:37], v[188:191], v[208:211], v[34:37]
	v_mfma_f32_16x16x32_bf16 v[18:21], v[184:187], v[212:215], v[18:21]
	v_mfma_f32_16x16x32_bf16 v[18:21], v[188:191], v[220:223], v[18:21]
	v_mfma_f32_16x16x32_bf16 v[2:5], v[184:187], v[224:227], v[2:5]
	v_mfma_f32_16x16x32_bf16 v[2:5], v[188:191], v[228:231], v[2:5]
	s_setprio 0
	s_add_i32 s59, 0, 0x18000
	s_add_i32 s60, 0, 0x1c000
	v_add_u32_e32 v142, s59, v166
	v_add_u32_e32 v188, s60, v166
	ds_read_b128 v[130:133], v142
	ds_read_b128 v[134:137], v142 offset:1024
	ds_read_b128 v[138:141], v142 offset:2048
	ds_read_b128 v[142:145], v142 offset:3072
	ds_read_b128 v[162:165], v188
	ds_read_b128 v[180:183], v188 offset:1024
	ds_read_b128 v[184:187], v188 offset:2048
	ds_read_b128 v[188:191], v188 offset:3072
	ds_read_b128 v[196:199], v179 offset:32768
	ds_read_b128 v[200:203], v179 offset:33792
	ds_read_b128 v[204:207], v179 offset:34816
	ds_read_b128 v[208:211], v179 offset:35840
	ds_read_b128 v[212:215], v179 offset:36864
	ds_read_b128 v[220:223], v179 offset:37888
	ds_read_b128 v[224:227], v179 offset:38912
	ds_read_b128 v[228:231], v179 offset:39936
	s_add_u32 vcc_lo, s42, 0x100000
	s_addc_u32 vcc_hi, s43, 0
	s_add_i32 m0, s24, 0x4000
	s_nop 0
	global_load_lds_dwordx4 v146, vcc
	s_add_i32 m0, s24, 0x6000
	s_nop 0
	global_load_lds_dwordx4 v150, vcc
	s_sleep 2
	s_waitcnt lgkmcnt(0)
	s_waitcnt vmcnt(8)
	s_barrier
; #define PG8_STAGE(bufoff, gbase, voff) do { _Pragma("unroll") for (int _i = 0; _i < 2; ++_i) \
;         __builtin_amdgcn_global_load_lds((const unsigned*)((const char*)(gbase) + (voff)[_i]), (PG8_LAS unsigned*)(lds + (bufoff) + ldsw + _i * 8192), 16, 0, 0); } while (0)
; #define PG8_LDA(dst, b, h) do { _Pragma("unroll") for (int m = 0; m < 4; ++m) _Pragma("unroll") for (int k = 0; k < 2; ++k) dst[m][k] = *(const PG8_LAS bf16x8*)(lds + PG8_SA(b, h) + aoff + m * 2048 + k * 1024); } while (0)
; #define PG8_MMA(ai, bj, At, Bt) do { __builtin_amdgcn_s_setprio(1); _Pragma("unroll") for (int m = 0; m < 4; ++m) _Pragma("unroll") for (int n = 0; n < 2; ++n) _Pragma("unroll") for (int k = 0; k < 2; ++k) \
;         acc[ai][bj][m][n] = __builtin_amdgcn_mfma_f32_16x16x32_bf16(Bt[n][k], At[m][k], acc[ai][bj][m][n], 0, 0, 0); __builtin_amdgcn_s_setprio(0); } while (0)
; #define PG8_WAIT_V(n) asm volatile("s_waitcnt vmcnt(" #n ")" ::: "memory")
; #define PG8_WAIT_L(n) asm volatile("s_waitcnt lgkmcnt(" #n ")" ::: "memory")
; #define PG8_BAR __builtin_amdgcn_s_barrier()
; #define PG8_SCHED __builtin_amdgcn_sched_barrier(0)
; template <class Epi, class Sched, bool ALIGN_EPI = false, bool SP2 = false>
; __device__ __forceinline__ void gemm_phase(PG8_LAS unsigned char* lds, const Gemm g, const Sched& S, const Epi& E) {
;     ...
;             PG8_WAIT_V(8); PG8_WAIT_L(0); PG8_BAR; PG8_MMA(0, 0, At, B0); PG8_MMA(0, 1, At, B1); PG8_BAR; PG8_SCHED;
;             PG8_LDA(At, 1, 1); PG8_STAGE(PG8_SB(1, 0), b3, voffB); PG8_STAGE(PG8_SB(1, 1), b3 + hstep, voffB); PG8_STAGE(PG8_SA(1, 0), a3, voffA);
;             PG8_WAIT_V(8); PG8_WAIT_L(0); PG8_BAR; PG8_MMA(1, 0, At, B0); PG8_MMA(1, 1, At, B1); PG8_BAR; PG8_SCHED;
	s_setprio 2
	v_mfma_f32_16x16x32_bf16 v[126:129], v[130:133], v[196:199], v[126:129]
	v_mfma_f32_16x16x32_bf16 v[126:129], v[134:137], v[200:203], v[126:129]
	v_mfma_f32_16x16x32_bf16 v[110:113], v[130:133], v[204:207], v[110:113]
	v_mfma_f32_16x16x32_bf16 v[110:113], v[134:137], v[208:211], v[110:113]
	v_mfma_f32_16x16x32_bf16 v[94:97], v[130:133], v[212:215], v[94:97]
	v_mfma_f32_16x16x32_bf16 v[94:97], v[134:137], v[220:223], v[94:97]
	v_mfma_f32_16x16x32_bf16 v[78:81], v[130:133], v[224:227], v[78:81]
	v_mfma_f32_16x16x32_bf16 v[78:81], v[134:137], v[228:231], v[78:81]
	v_mfma_f32_16x16x32_bf16 v[122:125], v[138:141], v[196:199], v[122:125]
	v_mfma_f32_16x16x32_bf16 v[122:125], v[142:145], v[200:203], v[122:125]
	v_mfma_f32_16x16x32_bf16 v[106:109], v[138:141], v[204:207], v[106:109]
	v_mfma_f32_16x16x32_bf16 v[106:109], v[142:145], v[208:211], v[106:109]
	v_mfma_f32_16x16x32_bf16 v[90:93], v[138:141], v[212:215], v[90:93]
	v_mfma_f32_16x16x32_bf16 v[90:93], v[142:145], v[220:223], v[90:93]
	v_mfma_f32_16x16x32_bf16 v[74:77], v[138:141], v[224:227], v[74:77]
	v_mfma_f32_16x16x32_bf16 v[74:77], v[142:145], v[228:231], v[74:77]
	v_mfma_f32_16x16x32_bf16 v[118:121], v[162:165], v[196:199], v[118:121]
	v_mfma_f32_16x16x32_bf16 v[118:121], v[180:183], v[200:203], v[118:121]
	v_mfma_f32_16x16x32_bf16 v[102:105], v[162:165], v[204:207], v[102:105]
	v_mfma_f32_16x16x32_bf16 v[102:105], v[180:183], v[208:211], v[102:105]
	v_mfma_f32_16x16x32_bf16 v[86:89], v[162:165], v[212:215], v[86:89]
	v_mfma_f32_16x16x32_bf16 v[86:89], v[180:183], v[220:223], v[86:89]
	v_mfma_f32_16x16x32_bf16 v[70:73], v[162:165], v[224:227], v[70:73]
	v_mfma_f32_16x16x32_bf16 v[70:73], v[180:183], v[228:231], v[70:73]
	v_mfma_f32_16x16x32_bf16 v[114:117], v[184:187], v[196:199], v[114:117]
	v_mfma_f32_16x16x32_bf16 v[114:117], v[188:191], v[200:203], v[114:117]
	v_mfma_f32_16x16x32_bf16 v[98:101], v[184:187], v[204:207], v[98:101]
	v_mfma_f32_16x16x32_bf16 v[98:101], v[188:191], v[208:211], v[98:101]
	v_mfma_f32_16x16x32_bf16 v[82:85], v[184:187], v[212:215], v[82:85]
	v_mfma_f32_16x16x32_bf16 v[82:85], v[188:191], v[220:223], v[82:85]
	v_mfma_f32_16x16x32_bf16 v[66:69], v[184:187], v[224:227], v[66:69]
	v_mfma_f32_16x16x32_bf16 v[66:69], v[188:191], v[228:231], v[66:69]
	s_setprio 0
	ds_read_b128 v[196:199], v179 offset:49152
	ds_read_b128 v[200:203], v179 offset:50176
	ds_read_b128 v[204:207], v179 offset:51200
	ds_read_b128 v[208:211], v179 offset:52224
	ds_read_b128 v[212:215], v179 offset:53248
	ds_read_b128 v[220:223], v179 offset:54272
	ds_read_b128 v[224:227], v179 offset:55296
	ds_read_b128 v[228:231], v179 offset:56320
	s_add_u32 s60, s40, 0x80
	s_addc_u32 s61, s41, 0
	s_add_u32 vcc_lo, s60, 0x100000
	s_addc_u32 vcc_hi, s61, 0
	s_add_i32 m0, s24, 0x18000
	s_nop 0
	global_load_lds_dwordx4 v148, s[60:61]
	s_add_i32 m0, s24, 0x1a000
	s_nop 0
	global_load_lds_dwordx4 v152, s[60:61]
	s_add_i32 m0, s24, 0x1c000
	s_nop 0
	global_load_lds_dwordx4 v148, vcc
	s_add_i32 m0, s24, 0x1e000
	s_nop 0
	global_load_lds_dwordx4 v152, vcc
	s_add_u32 s60, s42, 0x80
	s_addc_u32 s61, s43, 0
	s_add_i32 m0, s24, 0x8000
	s_nop 0
	global_load_lds_dwordx4 v146, s[60:61]
	s_add_i32 m0, s24, 0xa000
	s_nop 0
	global_load_lds_dwordx4 v150, s[60:61]
	s_sleep 2
	s_waitcnt lgkmcnt(0)
	s_waitcnt vmcnt(8)
	s_barrier
	s_setprio 2
	v_mfma_f32_16x16x32_bf16 v[62:65], v[130:133], v[196:199], v[62:65]
	v_mfma_f32_16x16x32_bf16 v[62:65], v[134:137], v[200:203], v[62:65]
	v_mfma_f32_16x16x32_bf16 v[46:49], v[130:133], v[204:207], v[46:49]
	v_mfma_f32_16x16x32_bf16 v[46:49], v[134:137], v[208:211], v[46:49]
	v_mfma_f32_16x16x32_bf16 v[30:33], v[130:133], v[212:215], v[30:33]
	v_mfma_f32_16x16x32_bf16 v[30:33], v[134:137], v[220:223], v[30:33]
	v_mfma_f32_16x16x32_bf16 v[14:17], v[130:133], v[224:227], v[14:17]
	v_mfma_f32_16x16x32_bf16 v[14:17], v[134:137], v[228:231], v[14:17]
	v_mfma_f32_16x16x32_bf16 v[58:61], v[138:141], v[196:199], v[58:61]
	v_mfma_f32_16x16x32_bf16 v[58:61], v[142:145], v[200:203], v[58:61]
	v_mfma_f32_16x16x32_bf16 v[42:45], v[138:141], v[204:207], v[42:45]
	v_mfma_f32_16x16x32_bf16 v[42:45], v[142:145], v[208:211], v[42:45]
	v_mfma_f32_16x16x32_bf16 v[26:29], v[138:141], v[212:215], v[26:29]
	v_mfma_f32_16x16x32_bf16 v[26:29], v[142:145], v[220:223], v[26:29]
	v_mfma_f32_16x16x32_bf16 v[10:13], v[138:141], v[224:227], v[10:13]
	v_mfma_f32_16x16x32_bf16 v[10:13], v[142:145], v[228:231], v[10:13]
	v_mfma_f32_16x16x32_bf16 v[54:57], v[162:165], v[196:199], v[54:57]
	v_mfma_f32_16x16x32_bf16 v[54:57], v[180:183], v[200:203], v[54:57]
	v_mfma_f32_16x16x32_bf16 v[38:41], v[162:165], v[204:207], v[38:41]
	v_mfma_f32_16x16x32_bf16 v[38:41], v[180:183], v[208:211], v[38:41]
	v_mfma_f32_16x16x32_bf16 v[22:25], v[162:165], v[212:215], v[22:25]
	v_mfma_f32_16x16x32_bf16 v[22:25], v[180:183], v[220:223], v[22:25]
	v_mfma_f32_16x16x32_bf16 v[6:9], v[162:165], v[224:227], v[6:9]
	v_mfma_f32_16x16x32_bf16 v[6:9], v[180:183], v[228:231], v[6:9]
	v_mfma_f32_16x16x32_bf16 v[50:53], v[184:187], v[196:199], v[50:53]
	v_mfma_f32_16x16x32_bf16 v[50:53], v[188:191], v[200:203], v[50:53]
	v_mfma_f32_16x16x32_bf16 v[34:37], v[184:187], v[204:207], v[34:37]
	v_mfma_f32_16x16x32_bf16 v[34:37], v[188:191], v[208:211], v[34:37]
	v_mfma_f32_16x16x32_bf16 v[18:21], v[184:187], v[212:215], v[18:21]
	v_mfma_f32_16x16x32_bf16 v[18:21], v[188:191], v[220:223], v[18:21]
	v_mfma_f32_16x16x32_bf16 v[2:5], v[184:187], v[224:227], v[2:5]
	v_mfma_f32_16x16x32_bf16 v[2:5], v[188:191], v[228:231], v[2:5]
	s_setprio 0
	s_add_i32 s58, s58, 2
	s_add_u32 s36, s36, 0x100
	s_addc_u32 s37, s37, 0
	s_add_u32 s56, s56, 0x100
	s_addc_u32 s57, s57, 0
	s_cmp_gt_u32 s58, 61
	s_cbranch_scc0 .Lf1_h1

; #define PG8_STAGE(bufoff, gbase, voff) do { _Pragma("unroll") for (int _i = 0; _i < 2; ++_i) \
;         __builtin_amdgcn_global_load_lds((const unsigned*)((const char*)(gbase) + (voff)[_i]), (PG8_LAS unsigned*)(lds + (bufoff) + ldsw + _i * 8192), 16, 0, 0); } while (0)
; #define PG8_LDA(dst, b, h) do { _Pragma("unroll") for (int m = 0; m < 4; ++m) _Pragma("unroll") for (int k = 0; k < 2; ++k) dst[m][k] = *(const PG8_LAS bf16x8*)(lds + PG8_SA(b, h) + aoff + m * 2048 + k * 1024); } while (0)
; #define PG8_LDB(dst, b, h) do { _Pragma("unroll") for (int n = 0; n < 2; ++n) _Pragma("unroll") for (int k = 0; k < 2; ++k) dst[n][k] = *(const PG8_LAS bf16x8*)(lds + PG8_SB(b, h) + boff + n * 2048 + k * 1024); } while (0)
; #define PG8_MMA(ai, bj, At, Bt) do { __builtin_amdgcn_s_setprio(1); _Pragma("unroll") for (int m = 0; m < 4; ++m) _Pragma("unroll") for (int n = 0; n < 2; ++n) _Pragma("unroll") for (int k = 0; k < 2; ++k) \
;         acc[ai][bj][m][n] = __builtin_amdgcn_mfma_f32_16x16x32_bf16(Bt[n][k], At[m][k], acc[ai][bj][m][n], 0, 0, 0); __builtin_amdgcn_s_setprio(0); } while (0)
; #define PG8_BAR __builtin_amdgcn_s_barrier()
; template <class Epi, class Sched, bool ALIGN_EPI = false, bool SP2 = false>
; __device__ __forceinline__ void gemm_phase(PG8_LAS unsigned char* lds, const Gemm g, const Sched& S, const Epi& E) {
;     ...
;             const bool last = (t == nt - 2);
;             const char* a1 = cA + (size_t)(t + 1) * kstep;
;             const char* a2 = last ? nA : cA + (size_t)(t + 2) * kstep; const char* b2 = last ? nB : cB + (size_t)(t + 2) * kstep;
;             const char* a3 = a2 + kstep; const char* b3 = b2 + kstep;
;             if (last && has_next) S.a_ready(nxt);
;             if constexpr (Epi::MIDK) { if (t == (nt >> 1)) { E.midk(acc, wr, fr); asm volatile("s_waitcnt lgkmcnt(0)" ::: "memory"); } }
;             if constexpr (SP2) {
;             PG8_LDB(B0, 0, 0); PG8_LDB(B1, 0, 1); PG8_SCHED; PG8_LDA(At, 0, 0); PG8_STAGE(PG8_SA(1, 1), a1 + hstep, voffA);
;             PG8_WAIT_V(8); PG8_WAIT_L(0); PG8_BAR; PG8_MMA(0, 0, At, B0); PG8_MMA(0, 1, At, B1); PG8_BAR; PG8_SCHED;
;             PG8_LDA(At, 0, 1); PG8_STAGE(PG8_SB(0, 0), b2, voffB); PG8_STAGE(PG8_SB(0, 1), b2 + hstep, voffB); PG8_STAGE(PG8_SA(0, 0), a2, voffA);
;             PG8_WAIT_V(8); PG8_WAIT_L(0); PG8_BAR; PG8_MMA(1, 0, At, B0); PG8_MMA(1, 1, At, B1); PG8_BAR; PG8_SCHED;
.LBB0_1321:
	ds_read_b128 v[128:131], v156
	ds_read_b128 v[132:135], v156 offset:1024
	ds_read_b128 v[150:153], v156 offset:2048
	ds_read_b128 v[162:165], v156 offset:3072
	ds_read_b128 v[166:169], v157
	ds_read_b128 v[170:173], v157 offset:1024
	ds_read_b128 v[174:177], v157 offset:2048
	ds_read_b128 v[178:181], v157 offset:3072
	s_add_u32 s20, s18, 0xffbfc080
	s_addc_u32 s21, s19, -1
	s_cmpk_eq_i32 s59, 0xfc
	s_cselect_b32 s23, s7, s21
	s_cselect_b32 s22, s6, s20
	s_cselect_b32 s21, s17, s58
	s_cselect_b32 s20, s16, s57
	ds_read_b128 v[182:185], v158
	ds_read_b128 v[186:189], v158 offset:1024
	ds_read_b128 v[190:193], v158 offset:2048
	ds_read_b128 v[194:197], v158 offset:3072
	ds_read_b128 v[198:201], v158 offset:4096
	ds_read_b128 v[202:205], v158 offset:5120
	ds_read_b128 v[206:209], v158 offset:6144
	ds_read_b128 v[210:213], v158 offset:7168
	s_add_i32 m0, s24, 0xc000
	s_nop 0
	global_load_lds_dwordx4 v136, s[18:19]
	s_add_i32 m0, s24, 0xe000
	s_nop 0
	global_load_lds_dwordx4 v140, s[18:19]
	s_waitcnt lgkmcnt(0)
	s_setprio 1
	v_mfma_f32_16x16x32_bf16 v[124:127], v[128:131], v[182:185], v[124:127]
	v_mfma_f32_16x16x32_bf16 v[124:127], v[132:135], v[186:189], v[124:127]
	v_mfma_f32_16x16x32_bf16 v[116:119], v[128:131], v[190:193], v[116:119]
	v_mfma_f32_16x16x32_bf16 v[116:119], v[132:135], v[194:197], v[116:119]
	v_mfma_f32_16x16x32_bf16 v[108:111], v[128:131], v[198:201], v[108:111]
	v_mfma_f32_16x16x32_bf16 v[108:111], v[132:135], v[202:205], v[108:111]
	v_mfma_f32_16x16x32_bf16 v[100:103], v[128:131], v[206:209], v[100:103]
	v_mfma_f32_16x16x32_bf16 v[100:103], v[132:135], v[210:213], v[100:103]
	v_mfma_f32_16x16x32_bf16 v[120:123], v[150:153], v[182:185], v[120:123]
	v_mfma_f32_16x16x32_bf16 v[120:123], v[162:165], v[186:189], v[120:123]
	v_mfma_f32_16x16x32_bf16 v[112:115], v[150:153], v[190:193], v[112:115]
	v_mfma_f32_16x16x32_bf16 v[112:115], v[162:165], v[194:197], v[112:115]
	v_mfma_f32_16x16x32_bf16 v[104:107], v[150:153], v[198:201], v[104:107]
	v_mfma_f32_16x16x32_bf16 v[104:107], v[162:165], v[202:205], v[104:107]
	v_mfma_f32_16x16x32_bf16 v[96:99], v[150:153], v[206:209], v[96:99]
	v_mfma_f32_16x16x32_bf16 v[96:99], v[162:165], v[210:213], v[96:99]
	v_mfma_f32_16x16x32_bf16 v[68:71], v[166:169], v[182:185], v[68:71]
	v_mfma_f32_16x16x32_bf16 v[68:71], v[170:173], v[186:189], v[68:71]
	v_mfma_f32_16x16x32_bf16 v[52:55], v[166:169], v[190:193], v[52:55]
	v_mfma_f32_16x16x32_bf16 v[52:55], v[170:173], v[194:197], v[52:55]
	v_mfma_f32_16x16x32_bf16 v[44:47], v[166:169], v[198:201], v[44:47]
	v_mfma_f32_16x16x32_bf16 v[44:47], v[170:173], v[202:205], v[44:47]
	v_mfma_f32_16x16x32_bf16 v[36:39], v[166:169], v[206:209], v[36:39]
	v_mfma_f32_16x16x32_bf16 v[36:39], v[170:173], v[210:213], v[36:39]
	v_mfma_f32_16x16x32_bf16 v[64:67], v[174:177], v[182:185], v[64:67]
	v_mfma_f32_16x16x32_bf16 v[64:67], v[178:181], v[186:189], v[64:67]
	v_mfma_f32_16x16x32_bf16 v[48:51], v[174:177], v[190:193], v[48:51]
	v_mfma_f32_16x16x32_bf16 v[48:51], v[178:181], v[194:197], v[48:51]
	v_mfma_f32_16x16x32_bf16 v[40:43], v[174:177], v[198:201], v[40:43]
	v_mfma_f32_16x16x32_bf16 v[40:43], v[178:181], v[202:205], v[40:43]
	v_mfma_f32_16x16x32_bf16 v[32:35], v[174:177], v[206:209], v[32:35]
	v_mfma_f32_16x16x32_bf16 v[32:35], v[178:181], v[210:213], v[32:35]
	s_setprio 0
	s_waitcnt vmcnt(8)
	s_barrier
	ds_read_b128 v[182:185], v158 offset:16384
	ds_read_b128 v[186:189], v158 offset:17408
	ds_read_b128 v[190:193], v158 offset:18432
	ds_read_b128 v[194:197], v158 offset:19456
	ds_read_b128 v[198:201], v158 offset:20480
	ds_read_b128 v[202:205], v158 offset:21504
	ds_read_b128 v[206:209], v158 offset:22528
	ds_read_b128 v[210:213], v158 offset:23552
	s_add_u32 vcc_lo, s20, 0x404000
	s_addc_u32 vcc_hi, s21, 0
	s_add_i32 m0, s24, 0x10000
	s_nop 0
	global_load_lds_dwordx4 v138, s[20:21]
	s_add_i32 m0, s24, 0x12000
	s_nop 0
	global_load_lds_dwordx4 v142, s[20:21]
	s_add_i32 m0, s24, 0x14000
	s_nop 0
	global_load_lds_dwordx4 v138, vcc
	s_add_i32 m0, s24, 0x16000
	s_nop 0
	global_load_lds_dwordx4 v142, vcc
	s_mov_b32 m0, s24
	s_nop 0
	global_load_lds_dwordx4 v136, s[22:23]
	s_add_i32 m0, s24, 0x2000
	s_nop 0
	global_load_lds_dwordx4 v140, s[22:23]
	s_waitcnt lgkmcnt(0)
	s_setprio 1
	v_mfma_f32_16x16x32_bf16 v[92:95], v[128:131], v[182:185], v[92:95]
	v_mfma_f32_16x16x32_bf16 v[92:95], v[132:135], v[186:189], v[92:95]
	v_mfma_f32_16x16x32_bf16 v[84:87], v[128:131], v[190:193], v[84:87]
	v_mfma_f32_16x16x32_bf16 v[84:87], v[132:135], v[194:197], v[84:87]
	v_mfma_f32_16x16x32_bf16 v[76:79], v[128:131], v[198:201], v[76:79]
	v_mfma_f32_16x16x32_bf16 v[76:79], v[132:135], v[202:205], v[76:79]
	v_mfma_f32_16x16x32_bf16 v[60:63], v[128:131], v[206:209], v[60:63]
	v_mfma_f32_16x16x32_bf16 v[60:63], v[132:135], v[210:213], v[60:63]
	v_mfma_f32_16x16x32_bf16 v[88:91], v[150:153], v[182:185], v[88:91]
	v_mfma_f32_16x16x32_bf16 v[88:91], v[162:165], v[186:189], v[88:91]
	v_mfma_f32_16x16x32_bf16 v[80:83], v[150:153], v[190:193], v[80:83]
	v_mfma_f32_16x16x32_bf16 v[80:83], v[162:165], v[194:197], v[80:83]
	v_mfma_f32_16x16x32_bf16 v[72:75], v[150:153], v[198:201], v[72:75]
	v_mfma_f32_16x16x32_bf16 v[72:75], v[162:165], v[202:205], v[72:75]
	v_mfma_f32_16x16x32_bf16 v[56:59], v[150:153], v[206:209], v[56:59]
	v_mfma_f32_16x16x32_bf16 v[56:59], v[162:165], v[210:213], v[56:59]
	v_mfma_f32_16x16x32_bf16 v[28:31], v[166:169], v[182:185], v[28:31]
	v_mfma_f32_16x16x32_bf16 v[28:31], v[170:173], v[186:189], v[28:31]
	v_mfma_f32_16x16x32_bf16 v[20:23], v[166:169], v[190:193], v[20:23]
	v_mfma_f32_16x16x32_bf16 v[20:23], v[170:173], v[194:197], v[20:23]
	v_mfma_f32_16x16x32_bf16 v[12:15], v[166:169], v[198:201], v[12:15]
	v_mfma_f32_16x16x32_bf16 v[12:15], v[170:173], v[202:205], v[12:15]
	v_mfma_f32_16x16x32_bf16 v[4:7], v[166:169], v[206:209], v[4:7]
	v_mfma_f32_16x16x32_bf16 v[4:7], v[170:173], v[210:213], v[4:7]
	v_mfma_f32_16x16x32_bf16 v[24:27], v[174:177], v[182:185], v[24:27]
	v_mfma_f32_16x16x32_bf16 v[24:27], v[178:181], v[186:189], v[24:27]
	v_mfma_f32_16x16x32_bf16 v[16:19], v[174:177], v[190:193], v[16:19]
	v_mfma_f32_16x16x32_bf16 v[16:19], v[178:181], v[194:197], v[16:19]
	v_mfma_f32_16x16x32_bf16 v[8:11], v[174:177], v[198:201], v[8:11]
	v_mfma_f32_16x16x32_bf16 v[8:11], v[178:181], v[202:205], v[8:11]
	v_mfma_f32_16x16x32_bf16 v[0:3], v[174:177], v[206:209], v[0:3]
	v_mfma_f32_16x16x32_bf16 v[0:3], v[178:181], v[210:213], v[0:3]
	s_setprio 0
	s_waitcnt vmcnt(8)
	s_barrier
; #define PG8_STAGE(bufoff, gbase, voff) do { _Pragma("unroll") for (int _i = 0; _i < 2; ++_i) \
;         __builtin_amdgcn_global_load_lds((const unsigned*)((const char*)(gbase) + (voff)[_i]), (PG8_LAS unsigned*)(lds + (bufoff) + ldsw + _i * 8192), 16, 0, 0); } while (0)
; #define PG8_LDA(dst, b, h) do { _Pragma("unroll") for (int m = 0; m < 4; ++m) _Pragma("unroll") for (int k = 0; k < 2; ++k) dst[m][k] = *(const PG8_LAS bf16x8*)(lds + PG8_SA(b, h) + aoff + m * 2048 + k * 1024); } while (0)
; #define PG8_LDB(dst, b, h) do { _Pragma("unroll") for (int n = 0; n < 2; ++n) _Pragma("unroll") for (int k = 0; k < 2; ++k) dst[n][k] = *(const PG8_LAS bf16x8*)(lds + PG8_SB(b, h) + boff + n * 2048 + k * 1024); } while (0)
; #define PG8_MMA(ai, bj, At, Bt) do { __builtin_amdgcn_s_setprio(1); _Pragma("unroll") for (int m = 0; m < 4; ++m) _Pragma("unroll") for (int n = 0; n < 2; ++n) _Pragma("unroll") for (int k = 0; k < 2; ++k) \
;         acc[ai][bj][m][n] = __builtin_amdgcn_mfma_f32_16x16x32_bf16(Bt[n][k], At[m][k], acc[ai][bj][m][n], 0, 0, 0); __builtin_amdgcn_s_setprio(0); } while (0)
; #define PG8_WAIT_V(n) asm volatile("s_waitcnt vmcnt(" #n ")" ::: "memory")
; #define PG8_WAIT_L(n) asm volatile("s_waitcnt lgkmcnt(" #n ")" ::: "memory")
; #define PG8_BAR __builtin_amdgcn_s_barrier()
; #define PG8_SCHED __builtin_amdgcn_sched_barrier(0)
; template <class Epi, class Sched, bool ALIGN_EPI = false, bool SP2 = false>
; __device__ __forceinline__ void gemm_phase(PG8_LAS unsigned char* lds, const Gemm g, const Sched& S, const Epi& E) {
;     ...
;             PG8_LDB(B0, 1, 0); PG8_LDB(B1, 1, 1); PG8_SCHED; PG8_LDA(At, 1, 0); PG8_STAGE(PG8_SA(0, 1), a2 + hstep, voffA);
;             PG8_WAIT_V(8); PG8_WAIT_L(0); PG8_BAR; PG8_MMA(0, 0, At, B0); PG8_MMA(0, 1, At, B1); PG8_BAR; PG8_SCHED;
;             PG8_LDA(At, 1, 1); PG8_STAGE(PG8_SB(1, 0), b3, voffB); PG8_STAGE(PG8_SB(1, 1), b3 + hstep, voffB); PG8_STAGE(PG8_SA(1, 0), a3, voffA);
;             PG8_WAIT_V(8); PG8_WAIT_L(0); PG8_BAR; PG8_MMA(1, 0, At, B0); PG8_MMA(1, 1, At, B1); PG8_BAR; PG8_SCHED;
	ds_read_b128 v[128:131], v159
	ds_read_b128 v[132:135], v159 offset:1024
	ds_read_b128 v[150:153], v159 offset:2048
	ds_read_b128 v[162:165], v159 offset:3072
	ds_read_b128 v[166:169], v160
	ds_read_b128 v[170:173], v160 offset:1024
	ds_read_b128 v[174:177], v160 offset:2048
	ds_read_b128 v[178:181], v160 offset:3072
	ds_read_b128 v[182:185], v158 offset:32768
	ds_read_b128 v[186:189], v158 offset:33792
	ds_read_b128 v[190:193], v158 offset:34816
	ds_read_b128 v[194:197], v158 offset:35840
	ds_read_b128 v[198:201], v158 offset:36864
	ds_read_b128 v[202:205], v158 offset:37888
	ds_read_b128 v[206:209], v158 offset:38912
	ds_read_b128 v[210:213], v158 offset:39936
	s_add_u32 vcc_lo, s22, 0x404000
	s_addc_u32 vcc_hi, s23, 0
	s_add_i32 m0, s24, 0x4000
	s_nop 0
	global_load_lds_dwordx4 v136, vcc
	s_add_i32 m0, s24, 0x6000
	s_nop 0
	global_load_lds_dwordx4 v140, vcc
	s_waitcnt lgkmcnt(0)
	s_setprio 1
	v_mfma_f32_16x16x32_bf16 v[124:127], v[128:131], v[182:185], v[124:127]
	v_mfma_f32_16x16x32_bf16 v[124:127], v[132:135], v[186:189], v[124:127]
	v_mfma_f32_16x16x32_bf16 v[116:119], v[128:131], v[190:193], v[116:119]
	v_mfma_f32_16x16x32_bf16 v[116:119], v[132:135], v[194:197], v[116:119]
	v_mfma_f32_16x16x32_bf16 v[108:111], v[128:131], v[198:201], v[108:111]
	v_mfma_f32_16x16x32_bf16 v[108:111], v[132:135], v[202:205], v[108:111]
	v_mfma_f32_16x16x32_bf16 v[100:103], v[128:131], v[206:209], v[100:103]
	v_mfma_f32_16x16x32_bf16 v[100:103], v[132:135], v[210:213], v[100:103]
	v_mfma_f32_16x16x32_bf16 v[120:123], v[150:153], v[182:185], v[120:123]
	v_mfma_f32_16x16x32_bf16 v[120:123], v[162:165], v[186:189], v[120:123]
	v_mfma_f32_16x16x32_bf16 v[112:115], v[150:153], v[190:193], v[112:115]
	v_mfma_f32_16x16x32_bf16 v[112:115], v[162:165], v[194:197], v[112:115]
	v_mfma_f32_16x16x32_bf16 v[104:107], v[150:153], v[198:201], v[104:107]
	v_mfma_f32_16x16x32_bf16 v[104:107], v[162:165], v[202:205], v[104:107]
	v_mfma_f32_16x16x32_bf16 v[96:99], v[150:153], v[206:209], v[96:99]
	v_mfma_f32_16x16x32_bf16 v[96:99], v[162:165], v[210:213], v[96:99]
	v_mfma_f32_16x16x32_bf16 v[68:71], v[166:169], v[182:185], v[68:71]
	v_mfma_f32_16x16x32_bf16 v[68:71], v[170:173], v[186:189], v[68:71]
	v_mfma_f32_16x16x32_bf16 v[52:55], v[166:169], v[190:193], v[52:55]
	v_mfma_f32_16x16x32_bf16 v[52:55], v[170:173], v[194:197], v[52:55]
	v_mfma_f32_16x16x32_bf16 v[44:47], v[166:169], v[198:201], v[44:47]
	v_mfma_f32_16x16x32_bf16 v[44:47], v[170:173], v[202:205], v[44:47]
	v_mfma_f32_16x16x32_bf16 v[36:39], v[166:169], v[206:209], v[36:39]
	v_mfma_f32_16x16x32_bf16 v[36:39], v[170:173], v[210:213], v[36:39]
	v_mfma_f32_16x16x32_bf16 v[64:67], v[174:177], v[182:185], v[64:67]
	v_mfma_f32_16x16x32_bf16 v[64:67], v[178:181], v[186:189], v[64:67]
	v_mfma_f32_16x16x32_bf16 v[48:51], v[174:177], v[190:193], v[48:51]
	v_mfma_f32_16x16x32_bf16 v[48:51], v[178:181], v[194:197], v[48:51]
	v_mfma_f32_16x16x32_bf16 v[40:43], v[174:177], v[198:201], v[40:43]
	v_mfma_f32_16x16x32_bf16 v[40:43], v[178:181], v[202:205], v[40:43]
	v_mfma_f32_16x16x32_bf16 v[32:35], v[174:177], v[206:209], v[32:35]
	v_mfma_f32_16x16x32_bf16 v[32:35], v[178:181], v[210:213], v[32:35]
	s_setprio 0
	s_waitcnt vmcnt(8)
	s_barrier
	ds_read_b128 v[182:185], v158 offset:49152
	ds_read_b128 v[186:189], v158 offset:50176
	ds_read_b128 v[190:193], v158 offset:51200
	ds_read_b128 v[194:197], v158 offset:52224
	ds_read_b128 v[198:201], v158 offset:53248
	ds_read_b128 v[202:205], v158 offset:54272
	ds_read_b128 v[206:209], v158 offset:55296
	ds_read_b128 v[210:213], v158 offset:56320
	s_add_u32 s60, s20, 0x80
	s_addc_u32 s61, s21, 0
	s_add_u32 vcc_lo, s60, 0x404000
	s_addc_u32 vcc_hi, s61, 0
	s_add_i32 m0, s24, 0x18000
	s_nop 0
	global_load_lds_dwordx4 v138, s[60:61]
	s_add_i32 m0, s24, 0x1a000
	s_nop 0
	global_load_lds_dwordx4 v142, s[60:61]
	s_add_i32 m0, s24, 0x1c000
	s_nop 0
	global_load_lds_dwordx4 v138, vcc
	s_add_i32 m0, s24, 0x1e000
	s_nop 0
	global_load_lds_dwordx4 v142, vcc
	s_add_u32 s60, s22, 0x80
	s_addc_u32 s61, s23, 0
	s_add_i32 m0, s24, 0x8000
	s_nop 0
	global_load_lds_dwordx4 v136, s[60:61]
	s_add_i32 m0, s24, 0xa000
	s_nop 0
	global_load_lds_dwordx4 v140, s[60:61]
	s_waitcnt lgkmcnt(0)
	s_setprio 1
	v_mfma_f32_16x16x32_bf16 v[92:95], v[128:131], v[182:185], v[92:95]
	v_mfma_f32_16x16x32_bf16 v[92:95], v[132:135], v[186:189], v[92:95]
	v_mfma_f32_16x16x32_bf16 v[84:87], v[128:131], v[190:193], v[84:87]
	v_mfma_f32_16x16x32_bf16 v[84:87], v[132:135], v[194:197], v[84:87]
	v_mfma_f32_16x16x32_bf16 v[76:79], v[128:131], v[198:201], v[76:79]
	v_mfma_f32_16x16x32_bf16 v[76:79], v[132:135], v[202:205], v[76:79]
	v_mfma_f32_16x16x32_bf16 v[60:63], v[128:131], v[206:209], v[60:63]
	v_mfma_f32_16x16x32_bf16 v[60:63], v[132:135], v[210:213], v[60:63]
	v_mfma_f32_16x16x32_bf16 v[88:91], v[150:153], v[182:185], v[88:91]
	v_mfma_f32_16x16x32_bf16 v[88:91], v[162:165], v[186:189], v[88:91]
	v_mfma_f32_16x16x32_bf16 v[80:83], v[150:153], v[190:193], v[80:83]
	v_mfma_f32_16x16x32_bf16 v[80:83], v[162:165], v[194:197], v[80:83]
	v_mfma_f32_16x16x32_bf16 v[72:75], v[150:153], v[198:201], v[72:75]
	v_mfma_f32_16x16x32_bf16 v[72:75], v[162:165], v[202:205], v[72:75]
	v_mfma_f32_16x16x32_bf16 v[56:59], v[150:153], v[206:209], v[56:59]
	v_mfma_f32_16x16x32_bf16 v[56:59], v[162:165], v[210:213], v[56:59]
	v_mfma_f32_16x16x32_bf16 v[28:31], v[166:169], v[182:185], v[28:31]
	v_mfma_f32_16x16x32_bf16 v[28:31], v[170:173], v[186:189], v[28:31]
	v_mfma_f32_16x16x32_bf16 v[20:23], v[166:169], v[190:193], v[20:23]
	v_mfma_f32_16x16x32_bf16 v[20:23], v[170:173], v[194:197], v[20:23]
	v_mfma_f32_16x16x32_bf16 v[12:15], v[166:169], v[198:201], v[12:15]
	v_mfma_f32_16x16x32_bf16 v[12:15], v[170:173], v[202:205], v[12:15]
	v_mfma_f32_16x16x32_bf16 v[4:7], v[166:169], v[206:209], v[4:7]
	v_mfma_f32_16x16x32_bf16 v[4:7], v[170:173], v[210:213], v[4:7]
	v_mfma_f32_16x16x32_bf16 v[24:27], v[174:177], v[182:185], v[24:27]
	v_mfma_f32_16x16x32_bf16 v[24:27], v[178:181], v[186:189], v[24:27]
	v_mfma_f32_16x16x32_bf16 v[16:19], v[174:177], v[190:193], v[16:19]
	v_mfma_f32_16x16x32_bf16 v[16:19], v[178:181], v[194:197], v[16:19]
	v_mfma_f32_16x16x32_bf16 v[8:11], v[174:177], v[198:201], v[8:11]
	v_mfma_f32_16x16x32_bf16 v[8:11], v[178:181], v[202:205], v[8:11]
	v_mfma_f32_16x16x32_bf16 v[0:3], v[174:177], v[206:209], v[0:3]
	v_mfma_f32_16x16x32_bf16 v[0:3], v[178:181], v[210:213], v[0:3]
	s_setprio 0
	s_waitcnt vmcnt(8)
	s_barrier
	s_add_i32 s59, s59, 2
	s_add_u32 s18, s18, 0x100
	s_addc_u32 s19, s19, 0
	s_add_u32 s57, s57, 0x100
	s_addc_u32 s58, s58, 0
	s_cmpk_gt_u32 s59, 0xfd
	s_cbranch_scc0 .LBB0_1321
	s_branch .Lf2_exit
; #define PG8_STAGE(bufoff, gbase, voff) do { _Pragma("unroll") for (int _i = 0; _i < 2; ++_i) \
;         __builtin_amdgcn_global_load_lds((const unsigned*)((const char*)(gbase) + (voff)[_i]), (PG8_LAS unsigned*)(lds + (bufoff) + ldsw + _i * 8192), 16, 0, 0); } while (0)
; #define PG8_LDA(dst, b, h) do { _Pragma("unroll") for (int m = 0; m < 4; ++m) _Pragma("unroll") for (int k = 0; k < 2; ++k) dst[m][k] = *(const PG8_LAS bf16x8*)(lds + PG8_SA(b, h) + aoff + m * 2048 + k * 1024); } while (0)
; #define PG8_LDB(dst, b, h) do { _Pragma("unroll") for (int n = 0; n < 2; ++n) _Pragma("unroll") for (int k = 0; k < 2; ++k) dst[n][k] = *(const PG8_LAS bf16x8*)(lds + PG8_SB(b, h) + boff + n * 2048 + k * 1024); } while (0)
; #define PG8_MMA(ai, bj, At, Bt) do { __builtin_amdgcn_s_setprio(1); _Pragma("unroll") for (int m = 0; m < 4; ++m) _Pragma("unroll") for (int n = 0; n < 2; ++n) _Pragma("unroll") for (int k = 0; k < 2; ++k) \
;         acc[ai][bj][m][n] = __builtin_amdgcn_mfma_f32_16x16x32_bf16(Bt[n][k], At[m][k], acc[ai][bj][m][n], 0, 0, 0); __builtin_amdgcn_s_setprio(0); } while (0)
; #define PG8_WAIT_V(n) asm volatile("s_waitcnt vmcnt(" #n ")" ::: "memory")
; #define PG8_WAIT_L(n) asm volatile("s_waitcnt lgkmcnt(" #n ")" ::: "memory")
; template <class Epi, class Sched, bool ALIGN_EPI = false, bool SP2 = false>
; __device__ __forceinline__ void gemm_phase(PG8_LAS unsigned char* lds, const Gemm g, const Sched& S, const Epi& E) {
;     ...
;             const bool last = (t == nt - 2);
;             const char* a1 = cA + (size_t)(t + 1) * kstep;
;             const char* a2 = last ? nA : cA + (size_t)(t + 2) * kstep; const char* b2 = last ? nB : cB + (size_t)(t + 2) * kstep;
;             const char* a3 = a2 + kstep; const char* b3 = b2 + kstep;
;             if (last && has_next) S.a_ready(nxt);
;             if constexpr (Epi::MIDK) { if (t == (nt >> 1)) { E.midk(acc, wr, fr); asm volatile("s_waitcnt lgkmcnt(0)" ::: "memory"); } }
;             if constexpr (SP2) {
;             PG8_LDB(B0, 0, 0); PG8_LDB(B1, 0, 1); PG8_SCHED; PG8_LDA(At, 0, 0); PG8_STAGE(PG8_SA(1, 1), a1 + hstep, voffA);
;             PG8_WAIT_V(8); PG8_WAIT_L(0); PG8_BAR; PG8_MMA(0, 0, At, B0); PG8_MMA(0, 1, At, B1); PG8_BAR; PG8_SCHED;
;             PG8_LDA(At, 0, 1); PG8_STAGE(PG8_SB(0, 0), b2, voffB); PG8_STAGE(PG8_SB(0, 1), b2 + hstep, voffB); PG8_STAGE(PG8_SA(0, 0), a2, voffA);
.Lf2_h1:
	ds_read_b128 v[128:131], v156
	ds_read_b128 v[132:135], v156 offset:1024
	ds_read_b128 v[150:153], v156 offset:2048
	ds_read_b128 v[162:165], v156 offset:3072
	ds_read_b128 v[166:169], v157
	ds_read_b128 v[170:173], v157 offset:1024
	ds_read_b128 v[174:177], v157 offset:2048
	ds_read_b128 v[178:181], v157 offset:3072
	s_add_u32 s20, s18, 0xffbfc080
	s_addc_u32 s21, s19, -1
	s_cmpk_eq_i32 s59, 0xfc
	s_cselect_b32 s23, s7, s21
	s_cselect_b32 s22, s6, s20
	s_cselect_b32 s21, s17, s58
	s_cselect_b32 s20, s16, s57
	ds_read_b128 v[182:185], v158
	ds_read_b128 v[186:189], v158 offset:1024
	ds_read_b128 v[190:193], v158 offset:2048
	ds_read_b128 v[194:197], v158 offset:3072
	ds_read_b128 v[198:201], v158 offset:4096
	ds_read_b128 v[202:205], v158 offset:5120
	ds_read_b128 v[206:209], v158 offset:6144
	ds_read_b128 v[210:213], v158 offset:7168
	s_add_i32 m0, s24, 0xc000
	s_nop 0
	global_load_lds_dwordx4 v136, s[18:19]
	s_add_i32 m0, s24, 0xe000
	s_nop 0
	global_load_lds_dwordx4 v140, s[18:19]
	s_sleep 2
	s_waitcnt lgkmcnt(0)
	s_waitcnt vmcnt(8)
	s_barrier
	s_setprio 2
	v_mfma_f32_16x16x32_bf16 v[124:127], v[128:131], v[182:185], v[124:127]
	v_mfma_f32_16x16x32_bf16 v[124:127], v[132:135], v[186:189], v[124:127]
	v_mfma_f32_16x16x32_bf16 v[116:119], v[128:131], v[190:193], v[116:119]
	v_mfma_f32_16x16x32_bf16 v[116:119], v[132:135], v[194:197], v[116:119]
	v_mfma_f32_16x16x32_bf16 v[108:111], v[128:131], v[198:201], v[108:111]
	v_mfma_f32_16x16x32_bf16 v[108:111], v[132:135], v[202:205], v[108:111]
	v_mfma_f32_16x16x32_bf16 v[100:103], v[128:131], v[206:209], v[100:103]
	v_mfma_f32_16x16x32_bf16 v[100:103], v[132:135], v[210:213], v[100:103]
	v_mfma_f32_16x16x32_bf16 v[120:123], v[150:153], v[182:185], v[120:123]
	v_mfma_f32_16x16x32_bf16 v[120:123], v[162:165], v[186:189], v[120:123]
	v_mfma_f32_16x16x32_bf16 v[112:115], v[150:153], v[190:193], v[112:115]
	v_mfma_f32_16x16x32_bf16 v[112:115], v[162:165], v[194:197], v[112:115]
	v_mfma_f32_16x16x32_bf16 v[104:107], v[150:153], v[198:201], v[104:107]
	v_mfma_f32_16x16x32_bf16 v[104:107], v[162:165], v[202:205], v[104:107]
	v_mfma_f32_16x16x32_bf16 v[96:99], v[150:153], v[206:209], v[96:99]
	v_mfma_f32_16x16x32_bf16 v[96:99], v[162:165], v[210:213], v[96:99]
	v_mfma_f32_16x16x32_bf16 v[68:71], v[166:169], v[182:185], v[68:71]
	v_mfma_f32_16x16x32_bf16 v[68:71], v[170:173], v[186:189], v[68:71]
	v_mfma_f32_16x16x32_bf16 v[52:55], v[166:169], v[190:193], v[52:55]
	v_mfma_f32_16x16x32_bf16 v[52:55], v[170:173], v[194:197], v[52:55]
	v_mfma_f32_16x16x32_bf16 v[44:47], v[166:169], v[198:201], v[44:47]
	v_mfma_f32_16x16x32_bf16 v[44:47], v[170:173], v[202:205], v[44:47]
	v_mfma_f32_16x16x32_bf16 v[36:39], v[166:169], v[206:209], v[36:39]
	v_mfma_f32_16x16x32_bf16 v[36:39], v[170:173], v[210:213], v[36:39]
	v_mfma_f32_16x16x32_bf16 v[64:67], v[174:177], v[182:185], v[64:67]
	v_mfma_f32_16x16x32_bf16 v[64:67], v[178:181], v[186:189], v[64:67]
	v_mfma_f32_16x16x32_bf16 v[48:51], v[174:177], v[190:193], v[48:51]
	v_mfma_f32_16x16x32_bf16 v[48:51], v[178:181], v[194:197], v[48:51]
	v_mfma_f32_16x16x32_bf16 v[40:43], v[174:177], v[198:201], v[40:43]
	v_mfma_f32_16x16x32_bf16 v[40:43], v[178:181], v[202:205], v[40:43]
	v_mfma_f32_16x16x32_bf16 v[32:35], v[174:177], v[206:209], v[32:35]
	v_mfma_f32_16x16x32_bf16 v[32:35], v[178:181], v[210:213], v[32:35]
	s_setprio 0
	ds_read_b128 v[182:185], v158 offset:16384
	ds_read_b128 v[186:189], v158 offset:17408
	ds_read_b128 v[190:193], v158 offset:18432
	ds_read_b128 v[194:197], v158 offset:19456
	ds_read_b128 v[198:201], v158 offset:20480
	ds_read_b128 v[202:205], v158 offset:21504
	ds_read_b128 v[206:209], v158 offset:22528
	ds_read_b128 v[210:213], v158 offset:23552
	s_add_u32 vcc_lo, s20, 0x404000
	s_addc_u32 vcc_hi, s21, 0
	s_add_i32 m0, s24, 0x10000
	s_nop 0
	global_load_lds_dwordx4 v138, s[20:21]
	s_add_i32 m0, s24, 0x12000
	s_nop 0
	global_load_lds_dwordx4 v142, s[20:21]
	s_add_i32 m0, s24, 0x14000
	s_nop 0
	global_load_lds_dwordx4 v138, vcc
	s_add_i32 m0, s24, 0x16000
	s_nop 0
	global_load_lds_dwordx4 v142, vcc
	s_mov_b32 m0, s24
	s_nop 0
	global_load_lds_dwordx4 v136, s[22:23]
	s_add_i32 m0, s24, 0x2000
	s_nop 0
	global_load_lds_dwordx4 v140, s[22:23]
	s_sleep 2
	s_waitcnt lgkmcnt(0)
	s_waitcnt vmcnt(8)
	s_barrier
; #define PG8_STAGE(bufoff, gbase, voff) do { _Pragma("unroll") for (int _i = 0; _i < 2; ++_i) \
;         __builtin_amdgcn_global_load_lds((const unsigned*)((const char*)(gbase) + (voff)[_i]), (PG8_LAS unsigned*)(lds + (bufoff) + ldsw + _i * 8192), 16, 0, 0); } while (0)
; #define PG8_LDA(dst, b, h) do { _Pragma("unroll") for (int m = 0; m < 4; ++m) _Pragma("unroll") for (int k = 0; k < 2; ++k) dst[m][k] = *(const PG8_LAS bf16x8*)(lds + PG8_SA(b, h) + aoff + m * 2048 + k * 1024); } while (0)
; #define PG8_LDB(dst, b, h) do { _Pragma("unroll") for (int n = 0; n < 2; ++n) _Pragma("unroll") for (int k = 0; k < 2; ++k) dst[n][k] = *(const PG8_LAS bf16x8*)(lds + PG8_SB(b, h) + boff + n * 2048 + k * 1024); } while (0)
; #define PG8_MMA(ai, bj, At, Bt) do { __builtin_amdgcn_s_setprio(1); _Pragma("unroll") for (int m = 0; m < 4; ++m) _Pragma("unroll") for (int n = 0; n < 2; ++n) _Pragma("unroll") for (int k = 0; k < 2; ++k) \
;         acc[ai][bj][m][n] = __builtin_amdgcn_mfma_f32_16x16x32_bf16(Bt[n][k], At[m][k], acc[ai][bj][m][n], 0, 0, 0); __builtin_amdgcn_s_setprio(0); } while (0)
; #define PG8_WAIT_V(n) asm volatile("s_waitcnt vmcnt(" #n ")" ::: "memory")
; #define PG8_WAIT_L(n) asm volatile("s_waitcnt lgkmcnt(" #n ")" ::: "memory")
; #define PG8_BAR __builtin_amdgcn_s_barrier()
; #define PG8_SCHED __builtin_amdgcn_sched_barrier(0)
; template <class Epi, class Sched, bool ALIGN_EPI = false, bool SP2 = false>
; __device__ __forceinline__ void gemm_phase(PG8_LAS unsigned char* lds, const Gemm g, const Sched& S, const Epi& E) {
;     ...
;             PG8_WAIT_V(8); PG8_WAIT_L(0); PG8_BAR; PG8_MMA(1, 0, At, B0); PG8_MMA(1, 1, At, B1); PG8_BAR; PG8_SCHED;
;             PG8_LDB(B0, 1, 0); PG8_LDB(B1, 1, 1); PG8_SCHED; PG8_LDA(At, 1, 0); PG8_STAGE(PG8_SA(0, 1), a2 + hstep, voffA);
;             PG8_WAIT_V(8); PG8_WAIT_L(0); PG8_BAR; PG8_MMA(0, 0, At, B0); PG8_MMA(0, 1, At, B1); PG8_BAR; PG8_SCHED;
	s_setprio 2
	v_mfma_f32_16x16x32_bf16 v[92:95], v[128:131], v[182:185], v[92:95]
	v_mfma_f32_16x16x32_bf16 v[92:95], v[132:135], v[186:189], v[92:95]
	v_mfma_f32_16x16x32_bf16 v[84:87], v[128:131], v[190:193], v[84:87]
	v_mfma_f32_16x16x32_bf16 v[84:87], v[132:135], v[194:197], v[84:87]
	v_mfma_f32_16x16x32_bf16 v[76:79], v[128:131], v[198:201], v[76:79]
	v_mfma_f32_16x16x32_bf16 v[76:79], v[132:135], v[202:205], v[76:79]
	v_mfma_f32_16x16x32_bf16 v[60:63], v[128:131], v[206:209], v[60:63]
	v_mfma_f32_16x16x32_bf16 v[60:63], v[132:135], v[210:213], v[60:63]
	v_mfma_f32_16x16x32_bf16 v[88:91], v[150:153], v[182:185], v[88:91]
	v_mfma_f32_16x16x32_bf16 v[88:91], v[162:165], v[186:189], v[88:91]
	v_mfma_f32_16x16x32_bf16 v[80:83], v[150:153], v[190:193], v[80:83]
	v_mfma_f32_16x16x32_bf16 v[80:83], v[162:165], v[194:197], v[80:83]
	v_mfma_f32_16x16x32_bf16 v[72:75], v[150:153], v[198:201], v[72:75]
	v_mfma_f32_16x16x32_bf16 v[72:75], v[162:165], v[202:205], v[72:75]
	v_mfma_f32_16x16x32_bf16 v[56:59], v[150:153], v[206:209], v[56:59]
	v_mfma_f32_16x16x32_bf16 v[56:59], v[162:165], v[210:213], v[56:59]
	v_mfma_f32_16x16x32_bf16 v[28:31], v[166:169], v[182:185], v[28:31]
	v_mfma_f32_16x16x32_bf16 v[28:31], v[170:173], v[186:189], v[28:31]
	v_mfma_f32_16x16x32_bf16 v[20:23], v[166:169], v[190:193], v[20:23]
	v_mfma_f32_16x16x32_bf16 v[20:23], v[170:173], v[194:197], v[20:23]
	v_mfma_f32_16x16x32_bf16 v[12:15], v[166:169], v[198:201], v[12:15]
	v_mfma_f32_16x16x32_bf16 v[12:15], v[170:173], v[202:205], v[12:15]
	v_mfma_f32_16x16x32_bf16 v[4:7], v[166:169], v[206:209], v[4:7]
	v_mfma_f32_16x16x32_bf16 v[4:7], v[170:173], v[210:213], v[4:7]
	v_mfma_f32_16x16x32_bf16 v[24:27], v[174:177], v[182:185], v[24:27]
	v_mfma_f32_16x16x32_bf16 v[24:27], v[178:181], v[186:189], v[24:27]
	v_mfma_f32_16x16x32_bf16 v[16:19], v[174:177], v[190:193], v[16:19]
	v_mfma_f32_16x16x32_bf16 v[16:19], v[178:181], v[194:197], v[16:19]
	v_mfma_f32_16x16x32_bf16 v[8:11], v[174:177], v[198:201], v[8:11]
	v_mfma_f32_16x16x32_bf16 v[8:11], v[178:181], v[202:205], v[8:11]
	v_mfma_f32_16x16x32_bf16 v[0:3], v[174:177], v[206:209], v[0:3]
	v_mfma_f32_16x16x32_bf16 v[0:3], v[178:181], v[210:213], v[0:3]
	s_setprio 0
	ds_read_b128 v[128:131], v159
	ds_read_b128 v[132:135], v159 offset:1024
	ds_read_b128 v[150:153], v159 offset:2048
	ds_read_b128 v[162:165], v159 offset:3072
	ds_read_b128 v[166:169], v160
	ds_read_b128 v[170:173], v160 offset:1024
	ds_read_b128 v[174:177], v160 offset:2048
	ds_read_b128 v[178:181], v160 offset:3072
	ds_read_b128 v[182:185], v158 offset:32768
	ds_read_b128 v[186:189], v158 offset:33792
	ds_read_b128 v[190:193], v158 offset:34816
	ds_read_b128 v[194:197], v158 offset:35840
	ds_read_b128 v[198:201], v158 offset:36864
	ds_read_b128 v[202:205], v158 offset:37888
	ds_read_b128 v[206:209], v158 offset:38912
	ds_read_b128 v[210:213], v158 offset:39936
	s_add_u32 vcc_lo, s22, 0x404000
	s_addc_u32 vcc_hi, s23, 0
	s_add_i32 m0, s24, 0x4000
	s_nop 0
	global_load_lds_dwordx4 v136, vcc
	s_add_i32 m0, s24, 0x6000
	s_nop 0
	global_load_lds_dwordx4 v140, vcc
	s_sleep 2
	s_waitcnt lgkmcnt(0)
	s_waitcnt vmcnt(8)
	s_barrier
; #define PG8_STAGE(bufoff, gbase, voff) do { _Pragma("unroll") for (int _i = 0; _i < 2; ++_i) \
;         __builtin_amdgcn_global_load_lds((const unsigned*)((const char*)(gbase) + (voff)[_i]), (PG8_LAS unsigned*)(lds + (bufoff) + ldsw + _i * 8192), 16, 0, 0); } while (0)
; #define PG8_LDA(dst, b, h) do { _Pragma("unroll") for (int m = 0; m < 4; ++m) _Pragma("unroll") for (int k = 0; k < 2; ++k) dst[m][k] = *(const PG8_LAS bf16x8*)(lds + PG8_SA(b, h) + aoff + m * 2048 + k * 1024); } while (0)
; #define PG8_MMA(ai, bj, At, Bt) do { __builtin_amdgcn_s_setprio(1); _Pragma("unroll") for (int m = 0; m < 4; ++m) _Pragma("unroll") for (int n = 0; n < 2; ++n) _Pragma("unroll") for (int k = 0; k < 2; ++k) \
;         acc[ai][bj][m][n] = __builtin_amdgcn_mfma_f32_16x16x32_bf16(Bt[n][k], At[m][k], acc[ai][bj][m][n], 0, 0, 0); __builtin_amdgcn_s_setprio(0); } while (0)
; #define PG8_WAIT_V(n) asm volatile("s_waitcnt vmcnt(" #n ")" ::: "memory")
; #define PG8_WAIT_L(n) asm volatile("s_waitcnt lgkmcnt(" #n ")" ::: "memory")
; #define PG8_BAR __builtin_amdgcn_s_barrier()
; #define PG8_SCHED __builtin_amdgcn_sched_barrier(0)
; template <class Epi, class Sched, bool ALIGN_EPI = false, bool SP2 = false>
; __device__ __forceinline__ void gemm_phase(PG8_LAS unsigned char* lds, const Gemm g, const Sched& S, const Epi& E) {
;     ...
;             PG8_WAIT_V(8); PG8_WAIT_L(0); PG8_BAR; PG8_MMA(0, 0, At, B0); PG8_MMA(0, 1, At, B1); PG8_BAR; PG8_SCHED;
;             PG8_LDA(At, 1, 1); PG8_STAGE(PG8_SB(1, 0), b3, voffB); PG8_STAGE(PG8_SB(1, 1), b3 + hstep, voffB); PG8_STAGE(PG8_SA(1, 0), a3, voffA);
;             PG8_WAIT_V(8); PG8_WAIT_L(0); PG8_BAR; PG8_MMA(1, 0, At, B0); PG8_MMA(1, 1, At, B1); PG8_BAR; PG8_SCHED;
	s_setprio 2
	v_mfma_f32_16x16x32_bf16 v[124:127], v[128:131], v[182:185], v[124:127]
	v_mfma_f32_16x16x32_bf16 v[124:127], v[132:135], v[186:189], v[124:127]
	v_mfma_f32_16x16x32_bf16 v[116:119], v[128:131], v[190:193], v[116:119]
	v_mfma_f32_16x16x32_bf16 v[116:119], v[132:135], v[194:197], v[116:119]
	v_mfma_f32_16x16x32_bf16 v[108:111], v[128:131], v[198:201], v[108:111]
	v_mfma_f32_16x16x32_bf16 v[108:111], v[132:135], v[202:205], v[108:111]
	v_mfma_f32_16x16x32_bf16 v[100:103], v[128:131], v[206:209], v[100:103]
	v_mfma_f32_16x16x32_bf16 v[100:103], v[132:135], v[210:213], v[100:103]
	v_mfma_f32_16x16x32_bf16 v[120:123], v[150:153], v[182:185], v[120:123]
	v_mfma_f32_16x16x32_bf16 v[120:123], v[162:165], v[186:189], v[120:123]
	v_mfma_f32_16x16x32_bf16 v[112:115], v[150:153], v[190:193], v[112:115]
	v_mfma_f32_16x16x32_bf16 v[112:115], v[162:165], v[194:197], v[112:115]
	v_mfma_f32_16x16x32_bf16 v[104:107], v[150:153], v[198:201], v[104:107]
	v_mfma_f32_16x16x32_bf16 v[104:107], v[162:165], v[202:205], v[104:107]
	v_mfma_f32_16x16x32_bf16 v[96:99], v[150:153], v[206:209], v[96:99]
	v_mfma_f32_16x16x32_bf16 v[96:99], v[162:165], v[210:213], v[96:99]
	v_mfma_f32_16x16x32_bf16 v[68:71], v[166:169], v[182:185], v[68:71]
	v_mfma_f32_16x16x32_bf16 v[68:71], v[170:173], v[186:189], v[68:71]
	v_mfma_f32_16x16x32_bf16 v[52:55], v[166:169], v[190:193], v[52:55]
	v_mfma_f32_16x16x32_bf16 v[52:55], v[170:173], v[194:197], v[52:55]
	v_mfma_f32_16x16x32_bf16 v[44:47], v[166:169], v[198:201], v[44:47]
	v_mfma_f32_16x16x32_bf16 v[44:47], v[170:173], v[202:205], v[44:47]
	v_mfma_f32_16x16x32_bf16 v[36:39], v[166:169], v[206:209], v[36:39]
	v_mfma_f32_16x16x32_bf16 v[36:39], v[170:173], v[210:213], v[36:39]
	v_mfma_f32_16x16x32_bf16 v[64:67], v[174:177], v[182:185], v[64:67]
	v_mfma_f32_16x16x32_bf16 v[64:67], v[178:181], v[186:189], v[64:67]
	v_mfma_f32_16x16x32_bf16 v[48:51], v[174:177], v[190:193], v[48:51]
	v_mfma_f32_16x16x32_bf16 v[48:51], v[178:181], v[194:197], v[48:51]
	v_mfma_f32_16x16x32_bf16 v[40:43], v[174:177], v[198:201], v[40:43]
	v_mfma_f32_16x16x32_bf16 v[40:43], v[178:181], v[202:205], v[40:43]
	v_mfma_f32_16x16x32_bf16 v[32:35], v[174:177], v[206:209], v[32:35]
	v_mfma_f32_16x16x32_bf16 v[32:35], v[178:181], v[210:213], v[32:35]
	s_setprio 0
	ds_read_b128 v[182:185], v158 offset:49152
	ds_read_b128 v[186:189], v158 offset:50176
	ds_read_b128 v[190:193], v158 offset:51200
	ds_read_b128 v[194:197], v158 offset:52224
	ds_read_b128 v[198:201], v158 offset:53248
	ds_read_b128 v[202:205], v158 offset:54272
	ds_read_b128 v[206:209], v158 offset:55296
	ds_read_b128 v[210:213], v158 offset:56320
	s_add_u32 s60, s20, 0x80
	s_addc_u32 s61, s21, 0
	s_add_u32 vcc_lo, s60, 0x404000
	s_addc_u32 vcc_hi, s61, 0
	s_add_i32 m0, s24, 0x18000
	s_nop 0
	global_load_lds_dwordx4 v138, s[60:61]
	s_add_i32 m0, s24, 0x1a000
	s_nop 0
	global_load_lds_dwordx4 v142, s[60:61]
	s_add_i32 m0, s24, 0x1c000
	s_nop 0
	global_load_lds_dwordx4 v138, vcc
	s_add_i32 m0, s24, 0x1e000
	s_nop 0
	global_load_lds_dwordx4 v142, vcc
	s_add_u32 s60, s22, 0x80
	s_addc_u32 s61, s23, 0
	s_add_i32 m0, s24, 0x8000
	s_nop 0
	global_load_lds_dwordx4 v136, s[60:61]
	s_add_i32 m0, s24, 0xa000
	s_nop 0
	global_load_lds_dwordx4 v140, s[60:61]
	s_sleep 2
	s_waitcnt lgkmcnt(0)
	s_waitcnt vmcnt(8)
	s_barrier
	s_setprio 2
	v_mfma_f32_16x16x32_bf16 v[92:95], v[128:131], v[182:185], v[92:95]
	v_mfma_f32_16x16x32_bf16 v[92:95], v[132:135], v[186:189], v[92:95]
	v_mfma_f32_16x16x32_bf16 v[84:87], v[128:131], v[190:193], v[84:87]
	v_mfma_f32_16x16x32_bf16 v[84:87], v[132:135], v[194:197], v[84:87]
	v_mfma_f32_16x16x32_bf16 v[76:79], v[128:131], v[198:201], v[76:79]
	v_mfma_f32_16x16x32_bf16 v[76:79], v[132:135], v[202:205], v[76:79]
	v_mfma_f32_16x16x32_bf16 v[60:63], v[128:131], v[206:209], v[60:63]
	v_mfma_f32_16x16x32_bf16 v[60:63], v[132:135], v[210:213], v[60:63]
	v_mfma_f32_16x16x32_bf16 v[88:91], v[150:153], v[182:185], v[88:91]
	v_mfma_f32_16x16x32_bf16 v[88:91], v[162:165], v[186:189], v[88:91]
	v_mfma_f32_16x16x32_bf16 v[80:83], v[150:153], v[190:193], v[80:83]
	v_mfma_f32_16x16x32_bf16 v[80:83], v[162:165], v[194:197], v[80:83]
	v_mfma_f32_16x16x32_bf16 v[72:75], v[150:153], v[198:201], v[72:75]
	v_mfma_f32_16x16x32_bf16 v[72:75], v[162:165], v[202:205], v[72:75]
	v_mfma_f32_16x16x32_bf16 v[56:59], v[150:153], v[206:209], v[56:59]
	v_mfma_f32_16x16x32_bf16 v[56:59], v[162:165], v[210:213], v[56:59]
	v_mfma_f32_16x16x32_bf16 v[28:31], v[166:169], v[182:185], v[28:31]
	v_mfma_f32_16x16x32_bf16 v[28:31], v[170:173], v[186:189], v[28:31]
	v_mfma_f32_16x16x32_bf16 v[20:23], v[166:169], v[190:193], v[20:23]
	v_mfma_f32_16x16x32_bf16 v[20:23], v[170:173], v[194:197], v[20:23]
	v_mfma_f32_16x16x32_bf16 v[12:15], v[166:169], v[198:201], v[12:15]
	v_mfma_f32_16x16x32_bf16 v[12:15], v[170:173], v[202:205], v[12:15]
	v_mfma_f32_16x16x32_bf16 v[4:7], v[166:169], v[206:209], v[4:7]
	v_mfma_f32_16x16x32_bf16 v[4:7], v[170:173], v[210:213], v[4:7]
	v_mfma_f32_16x16x32_bf16 v[24:27], v[174:177], v[182:185], v[24:27]
	v_mfma_f32_16x16x32_bf16 v[24:27], v[178:181], v[186:189], v[24:27]
	v_mfma_f32_16x16x32_bf16 v[16:19], v[174:177], v[190:193], v[16:19]
	v_mfma_f32_16x16x32_bf16 v[16:19], v[178:181], v[194:197], v[16:19]
	v_mfma_f32_16x16x32_bf16 v[8:11], v[174:177], v[198:201], v[8:11]
	v_mfma_f32_16x16x32_bf16 v[8:11], v[178:181], v[202:205], v[8:11]
	v_mfma_f32_16x16x32_bf16 v[0:3], v[174:177], v[206:209], v[0:3]
	v_mfma_f32_16x16x32_bf16 v[0:3], v[178:181], v[210:213], v[0:3]
	s_setprio 0
	s_add_i32 s59, s59, 2
	s_add_u32 s18, s18, 0x100
	s_addc_u32 s19, s19, 0
	s_add_u32 s57, s57, 0x100
	s_addc_u32 s58, s58, 0
	s_cmpk_gt_u32 s59, 0xfd
	s_cbranch_scc0 .Lf2_h1
